# knob: FFN-up / residual GEMM epilogues run at s_setprio 3 (staging stays 0, MFMA block 2)
# baseline (speedup 1.0000x reference)
.LBB0_26:
	s_setprio 3
	s_mul_i32 s1, s5, s82
	s_add_i32 s1, s1, s63
	s_ashr_i32 s3, s1, 31
	s_lshr_b32 s3, s3, 28
	s_add_i32 s3, s1, s3
	s_ashr_i32 s6, s3, 4
	s_and_b32 s3, s3, -16
	s_sub_i32 s1, s1, s3
	s_lshl_b32 s3, s6, 1
	s_and_b32 s6, s1, 1
	s_or_b32 s3, s6, s3
	v_readlane_b32 s6, v252, 35
	s_sub_i32 s8, 0x7f, s3
	v_readlane_b32 s7, v252, 36
	s_and_b64 s[6:7], s[6:7], exec
	s_cselect_b32 s6, s8, s3
	v_mov_b32_e32 v0, v222
	s_ashr_i32 s7, s6, 31
	v_and_b32_e32 v190, 0xffffff80, v0
	s_lshl_b64 s[6:7], s[6:7], 8
	v_ashrrev_i32_e32 v191, 31, v190
	v_lshl_add_u64 v[190:191], s[6:7], 0, v[190:191]
	s_lshl_b32 s1, s1, 6
	v_and_b32_e32 v185, 64, v0
	v_and_or_b32 v190, v0, 31, v190
	s_and_b32 s1, s1, 0xffffff80
	v_lshrrev_b32_e32 v0, 3, v0
	v_readlane_b32 s6, v252, 31
	s_ashr_i32 s3, s1, 31
	v_and_b32_e32 v0, 4, v0
	v_lshlrev_b64 v[190:191], 12, v[190:191]
	v_readlane_b32 s7, v252, 32
	v_or3_b32 v192, v0, v185, s1
	v_mov_b32_e32 v193, s3
	v_lshl_add_u64 v[190:191], s[6:7], 0, v[190:191]
	v_lshl_add_u64 v[190:191], v[192:193], 2, v[190:191]
	s_mov_b64 s[98:99], 0x20000
	v_lshl_add_u64 v[192:193], v[190:191], 0, 0
	v_lshl_add_u64 v[220:221], v[190:191], 0, 0
	global_load_dwordx4 v[194:197], v[192:193], off
	global_load_dwordx4 v[198:201], v[192:193], off offset:32
	global_load_dwordx4 v[202:205], v[192:193], off offset:64
	global_load_dwordx4 v[206:209], v[192:193], off offset:96
	global_load_dwordx4 v[216:219], v[192:193], off offset:128
	global_load_dwordx4 v[236:239], v[192:193], off offset:160
	global_load_dwordx4 v[240:243], v[192:193], off offset:192
	global_load_dwordx4 v[244:247], v[192:193], off offset:224
	s_waitcnt vmcnt(7)
	v_pk_fma_f32 v[114:115], v[114:115], 0.5, v[194:195] op_sel_hi:[1,0,1]
	v_pk_fma_f32 v[116:117], v[116:117], 0.5, v[196:197] op_sel_hi:[1,0,1]
	global_store_dwordx4 v[220:221], v[114:117], off
	v_lshl_add_u64 v[192:193], v[192:193], 0, s[98:99]
	global_load_dwordx4 v[194:197], v[192:193], off
	s_waitcnt vmcnt(8)
	v_pk_fma_f32 v[118:119], v[118:119], 0.5, v[198:199] op_sel_hi:[1,0,1]
	v_pk_fma_f32 v[120:121], v[120:121], 0.5, v[200:201] op_sel_hi:[1,0,1]
	global_store_dwordx4 v[220:221], v[118:121], off offset:32
	global_load_dwordx4 v[198:201], v[192:193], off offset:32
	s_waitcnt vmcnt(9)
	v_pk_fma_f32 v[122:123], v[122:123], 0.5, v[202:203] op_sel_hi:[1,0,1]
	v_pk_fma_f32 v[124:125], v[124:125], 0.5, v[204:205] op_sel_hi:[1,0,1]
	global_store_dwordx4 v[220:221], v[122:125], off offset:64
	global_load_dwordx4 v[202:205], v[192:193], off offset:64
	s_waitcnt vmcnt(10)
	v_pk_fma_f32 v[126:127], v[126:127], 0.5, v[206:207] op_sel_hi:[1,0,1]
	v_pk_fma_f32 v[128:129], v[128:129], 0.5, v[208:209] op_sel_hi:[1,0,1]
	global_store_dwordx4 v[220:221], v[126:129], off offset:96
	global_load_dwordx4 v[206:209], v[192:193], off offset:96
	s_waitcnt vmcnt(11)
	v_pk_fma_f32 v[98:99], v[98:99], 0.5, v[216:217] op_sel_hi:[1,0,1]
	v_pk_fma_f32 v[100:101], v[100:101], 0.5, v[218:219] op_sel_hi:[1,0,1]
	global_store_dwordx4 v[220:221], v[98:101], off offset:128
	global_load_dwordx4 v[216:219], v[192:193], off offset:128
	s_waitcnt vmcnt(12)
	v_pk_fma_f32 v[102:103], v[102:103], 0.5, v[236:237] op_sel_hi:[1,0,1]
	v_pk_fma_f32 v[104:105], v[104:105], 0.5, v[238:239] op_sel_hi:[1,0,1]
	global_store_dwordx4 v[220:221], v[102:105], off offset:160
	global_load_dwordx4 v[236:239], v[192:193], off offset:160
	s_waitcnt vmcnt(13)
	v_pk_fma_f32 v[106:107], v[106:107], 0.5, v[240:241] op_sel_hi:[1,0,1]
	v_pk_fma_f32 v[108:109], v[108:109], 0.5, v[242:243] op_sel_hi:[1,0,1]
	global_store_dwordx4 v[220:221], v[106:109], off offset:192
	global_load_dwordx4 v[240:243], v[192:193], off offset:192
	s_waitcnt vmcnt(14)
	v_pk_fma_f32 v[110:111], v[110:111], 0.5, v[244:245] op_sel_hi:[1,0,1]
	v_pk_fma_f32 v[112:113], v[112:113], 0.5, v[246:247] op_sel_hi:[1,0,1]
	global_store_dwordx4 v[220:221], v[110:113], off offset:224
	global_load_dwordx4 v[244:247], v[192:193], off offset:224
	s_waitcnt vmcnt(14)
	v_pk_fma_f32 v[82:83], v[82:83], 0.5, v[194:195] op_sel_hi:[1,0,1]
	v_pk_fma_f32 v[84:85], v[84:85], 0.5, v[196:197] op_sel_hi:[1,0,1]
	v_lshl_add_u64 v[220:221], v[220:221], 0, s[98:99]
	global_store_dwordx4 v[220:221], v[82:85], off
	v_lshl_add_u64 v[192:193], v[192:193], 0, s[98:99]
	global_load_dwordx4 v[194:197], v[192:193], off
	s_waitcnt vmcnt(14)
	v_pk_fma_f32 v[86:87], v[86:87], 0.5, v[198:199] op_sel_hi:[1,0,1]
	v_pk_fma_f32 v[88:89], v[88:89], 0.5, v[200:201] op_sel_hi:[1,0,1]
	global_store_dwordx4 v[220:221], v[86:89], off offset:32
	global_load_dwordx4 v[198:201], v[192:193], off offset:32
	s_waitcnt vmcnt(14)
	v_pk_fma_f32 v[90:91], v[90:91], 0.5, v[202:203] op_sel_hi:[1,0,1]
	v_pk_fma_f32 v[92:93], v[92:93], 0.5, v[204:205] op_sel_hi:[1,0,1]
	global_store_dwordx4 v[220:221], v[90:93], off offset:64
	global_load_dwordx4 v[202:205], v[192:193], off offset:64
	s_waitcnt vmcnt(14)
	v_pk_fma_f32 v[94:95], v[94:95], 0.5, v[206:207] op_sel_hi:[1,0,1]
	v_pk_fma_f32 v[96:97], v[96:97], 0.5, v[208:209] op_sel_hi:[1,0,1]
	global_store_dwordx4 v[220:221], v[94:97], off offset:96
	global_load_dwordx4 v[206:209], v[192:193], off offset:96
	s_waitcnt vmcnt(14)
	v_pk_fma_f32 v[66:67], v[66:67], 0.5, v[216:217] op_sel_hi:[1,0,1]
	v_pk_fma_f32 v[68:69], v[68:69], 0.5, v[218:219] op_sel_hi:[1,0,1]
	global_store_dwordx4 v[220:221], v[66:69], off offset:128
	global_load_dwordx4 v[216:219], v[192:193], off offset:128
	s_waitcnt vmcnt(14)
	v_pk_fma_f32 v[70:71], v[70:71], 0.5, v[236:237] op_sel_hi:[1,0,1]
	v_pk_fma_f32 v[72:73], v[72:73], 0.5, v[238:239] op_sel_hi:[1,0,1]
	global_store_dwordx4 v[220:221], v[70:73], off offset:160
	global_load_dwordx4 v[236:239], v[192:193], off offset:160
	s_waitcnt vmcnt(14)
	v_pk_fma_f32 v[74:75], v[74:75], 0.5, v[240:241] op_sel_hi:[1,0,1]
	v_pk_fma_f32 v[76:77], v[76:77], 0.5, v[242:243] op_sel_hi:[1,0,1]
	global_store_dwordx4 v[220:221], v[74:77], off offset:192
	global_load_dwordx4 v[240:243], v[192:193], off offset:192
	s_waitcnt vmcnt(14)
	v_pk_fma_f32 v[78:79], v[78:79], 0.5, v[244:245] op_sel_hi:[1,0,1]
	v_pk_fma_f32 v[80:81], v[80:81], 0.5, v[246:247] op_sel_hi:[1,0,1]
	global_store_dwordx4 v[220:221], v[78:81], off offset:224
	global_load_dwordx4 v[244:247], v[192:193], off offset:224
	s_waitcnt vmcnt(14)
	v_pk_fma_f32 v[50:51], v[50:51], 0.5, v[194:195] op_sel_hi:[1,0,1]
	v_pk_fma_f32 v[52:53], v[52:53], 0.5, v[196:197] op_sel_hi:[1,0,1]
	v_lshl_add_u64 v[220:221], v[220:221], 0, s[98:99]
	global_store_dwordx4 v[220:221], v[50:53], off
	v_lshl_add_u64 v[192:193], v[192:193], 0, s[98:99]
	global_load_dwordx4 v[194:197], v[192:193], off
	s_waitcnt vmcnt(14)
	v_pk_fma_f32 v[54:55], v[54:55], 0.5, v[198:199] op_sel_hi:[1,0,1]
	v_pk_fma_f32 v[56:57], v[56:57], 0.5, v[200:201] op_sel_hi:[1,0,1]
	global_store_dwordx4 v[220:221], v[54:57], off offset:32
	global_load_dwordx4 v[198:201], v[192:193], off offset:32
	s_waitcnt vmcnt(14)
	v_pk_fma_f32 v[58:59], v[58:59], 0.5, v[202:203] op_sel_hi:[1,0,1]
	v_pk_fma_f32 v[60:61], v[60:61], 0.5, v[204:205] op_sel_hi:[1,0,1]
	global_store_dwordx4 v[220:221], v[58:61], off offset:64
	global_load_dwordx4 v[202:205], v[192:193], off offset:64
	s_waitcnt vmcnt(14)
	v_pk_fma_f32 v[62:63], v[62:63], 0.5, v[206:207] op_sel_hi:[1,0,1]
	v_pk_fma_f32 v[64:65], v[64:65], 0.5, v[208:209] op_sel_hi:[1,0,1]
	global_store_dwordx4 v[220:221], v[62:65], off offset:96
	global_load_dwordx4 v[206:209], v[192:193], off offset:96
	s_waitcnt vmcnt(14)
	v_pk_fma_f32 v[34:35], v[34:35], 0.5, v[216:217] op_sel_hi:[1,0,1]
	v_pk_fma_f32 v[36:37], v[36:37], 0.5, v[218:219] op_sel_hi:[1,0,1]
	global_store_dwordx4 v[220:221], v[34:37], off offset:128
	global_load_dwordx4 v[216:219], v[192:193], off offset:128
	s_waitcnt vmcnt(14)
	v_pk_fma_f32 v[38:39], v[38:39], 0.5, v[236:237] op_sel_hi:[1,0,1]
	v_pk_fma_f32 v[40:41], v[40:41], 0.5, v[238:239] op_sel_hi:[1,0,1]
	global_store_dwordx4 v[220:221], v[38:41], off offset:160
	global_load_dwordx4 v[236:239], v[192:193], off offset:160
	s_waitcnt vmcnt(14)
	v_pk_fma_f32 v[42:43], v[42:43], 0.5, v[240:241] op_sel_hi:[1,0,1]
	v_pk_fma_f32 v[44:45], v[44:45], 0.5, v[242:243] op_sel_hi:[1,0,1]
	global_store_dwordx4 v[220:221], v[42:45], off offset:192
	global_load_dwordx4 v[240:243], v[192:193], off offset:192
	s_waitcnt vmcnt(14)
	v_pk_fma_f32 v[46:47], v[46:47], 0.5, v[244:245] op_sel_hi:[1,0,1]
	v_pk_fma_f32 v[48:49], v[48:49], 0.5, v[246:247] op_sel_hi:[1,0,1]
	global_store_dwordx4 v[220:221], v[46:49], off offset:224
	global_load_dwordx4 v[244:247], v[192:193], off offset:224
	s_waitcnt vmcnt(14)
	v_pk_fma_f32 v[18:19], v[18:19], 0.5, v[194:195] op_sel_hi:[1,0,1]
	v_pk_fma_f32 v[20:21], v[20:21], 0.5, v[196:197] op_sel_hi:[1,0,1]
	v_lshl_add_u64 v[220:221], v[220:221], 0, s[98:99]
	global_store_dwordx4 v[220:221], v[18:21], off
	s_waitcnt vmcnt(13)
	v_pk_fma_f32 v[22:23], v[22:23], 0.5, v[198:199] op_sel_hi:[1,0,1]
	v_pk_fma_f32 v[24:25], v[24:25], 0.5, v[200:201] op_sel_hi:[1,0,1]
	global_store_dwordx4 v[220:221], v[22:25], off offset:32
	s_waitcnt vmcnt(12)
	v_pk_fma_f32 v[26:27], v[26:27], 0.5, v[202:203] op_sel_hi:[1,0,1]
	v_pk_fma_f32 v[28:29], v[28:29], 0.5, v[204:205] op_sel_hi:[1,0,1]
	global_store_dwordx4 v[220:221], v[26:29], off offset:64
	s_waitcnt vmcnt(11)
	v_pk_fma_f32 v[30:31], v[30:31], 0.5, v[206:207] op_sel_hi:[1,0,1]
	v_pk_fma_f32 v[32:33], v[32:33], 0.5, v[208:209] op_sel_hi:[1,0,1]
	global_store_dwordx4 v[220:221], v[30:33], off offset:96
	s_waitcnt vmcnt(10)
	v_pk_fma_f32 v[2:3], v[2:3], 0.5, v[216:217] op_sel_hi:[1,0,1]
	v_pk_fma_f32 v[4:5], v[4:5], 0.5, v[218:219] op_sel_hi:[1,0,1]
	global_store_dwordx4 v[220:221], v[2:5], off offset:128
	s_waitcnt vmcnt(9)
	v_pk_fma_f32 v[6:7], v[6:7], 0.5, v[236:237] op_sel_hi:[1,0,1]
	v_pk_fma_f32 v[8:9], v[8:9], 0.5, v[238:239] op_sel_hi:[1,0,1]
	global_store_dwordx4 v[220:221], v[6:9], off offset:160
	s_waitcnt vmcnt(8)
	v_pk_fma_f32 v[10:11], v[10:11], 0.5, v[240:241] op_sel_hi:[1,0,1]
	v_pk_fma_f32 v[12:13], v[12:13], 0.5, v[242:243] op_sel_hi:[1,0,1]
	global_store_dwordx4 v[220:221], v[10:13], off offset:192
	s_waitcnt vmcnt(7)
	v_pk_fma_f32 v[14:15], v[14:15], 0.5, v[244:245] op_sel_hi:[1,0,1]
	v_pk_fma_f32 v[16:17], v[16:17], 0.5, v[246:247] op_sel_hi:[1,0,1]
	global_store_dwordx4 v[220:221], v[14:17], off offset:224
	s_mov_b32 s3, 0
	s_add_i32 s5, s5, 1
	v_mov_b32_e32 v114, 0
	v_mov_b32_e32 v115, 0
	v_mov_b32_e32 v116, 0
	v_mov_b32_e32 v117, 0
	v_mov_b32_e32 v118, 0
	v_mov_b32_e32 v119, 0
	v_mov_b32_e32 v120, 0
	v_mov_b32_e32 v121, 0
	v_mov_b32_e32 v122, 0
	v_mov_b32_e32 v123, 0
	v_mov_b32_e32 v124, 0
	v_mov_b32_e32 v125, 0
	v_mov_b32_e32 v126, 0
	v_mov_b32_e32 v127, 0
	v_mov_b32_e32 v128, 0
	v_mov_b32_e32 v129, 0
	v_mov_b32_e32 v98, 0
	v_mov_b32_e32 v99, 0
	v_mov_b32_e32 v100, 0
	v_mov_b32_e32 v101, 0
	v_mov_b32_e32 v102, 0
	v_mov_b32_e32 v103, 0
	v_mov_b32_e32 v104, 0
	v_mov_b32_e32 v105, 0
	v_mov_b32_e32 v106, 0
	v_mov_b32_e32 v107, 0
	v_mov_b32_e32 v108, 0
	v_mov_b32_e32 v109, 0
	v_mov_b32_e32 v110, 0
	v_mov_b32_e32 v111, 0
	v_mov_b32_e32 v112, 0
	v_mov_b32_e32 v113, 0
	v_mov_b32_e32 v82, 0
	v_mov_b32_e32 v83, 0
	v_mov_b32_e32 v84, 0
	v_mov_b32_e32 v85, 0
	v_mov_b32_e32 v86, 0
	v_mov_b32_e32 v87, 0
	v_mov_b32_e32 v88, 0
	v_mov_b32_e32 v89, 0
	v_mov_b32_e32 v90, 0
	v_mov_b32_e32 v91, 0
	v_mov_b32_e32 v92, 0
	v_mov_b32_e32 v93, 0
	v_mov_b32_e32 v94, 0
	v_mov_b32_e32 v95, 0
	v_mov_b32_e32 v96, 0
	v_mov_b32_e32 v97, 0
	v_mov_b32_e32 v66, 0
	v_mov_b32_e32 v67, 0
	v_mov_b32_e32 v68, 0
	v_mov_b32_e32 v69, 0
	v_mov_b32_e32 v70, 0
	v_mov_b32_e32 v71, 0
	v_mov_b32_e32 v72, 0
	v_mov_b32_e32 v73, 0
	v_mov_b32_e32 v74, 0
	v_mov_b32_e32 v75, 0
	v_mov_b32_e32 v76, 0
	v_mov_b32_e32 v77, 0
	v_mov_b32_e32 v78, 0
	v_mov_b32_e32 v79, 0
	v_mov_b32_e32 v80, 0
	v_mov_b32_e32 v81, 0
	v_mov_b32_e32 v50, 0
	v_mov_b32_e32 v51, 0
	v_mov_b32_e32 v52, 0
	v_mov_b32_e32 v53, 0
	v_mov_b32_e32 v54, 0
	v_mov_b32_e32 v55, 0
	v_mov_b32_e32 v56, 0
	v_mov_b32_e32 v57, 0
	v_mov_b32_e32 v58, 0
	v_mov_b32_e32 v59, 0
	v_mov_b32_e32 v60, 0
	v_mov_b32_e32 v61, 0
	v_mov_b32_e32 v62, 0
	v_mov_b32_e32 v63, 0
	v_mov_b32_e32 v64, 0
	v_mov_b32_e32 v65, 0
	v_mov_b32_e32 v34, 0
	v_mov_b32_e32 v35, 0
	v_mov_b32_e32 v36, 0
	v_mov_b32_e32 v37, 0
	v_mov_b32_e32 v38, 0
	v_mov_b32_e32 v39, 0
	v_mov_b32_e32 v40, 0
	v_mov_b32_e32 v41, 0
	v_mov_b32_e32 v42, 0
	v_mov_b32_e32 v43, 0
	v_mov_b32_e32 v44, 0
	v_mov_b32_e32 v45, 0
	v_mov_b32_e32 v46, 0
	v_mov_b32_e32 v47, 0
	v_mov_b32_e32 v48, 0
	v_mov_b32_e32 v49, 0
	v_mov_b32_e32 v18, 0
	v_mov_b32_e32 v19, 0
	v_mov_b32_e32 v20, 0
	v_mov_b32_e32 v21, 0
	v_mov_b32_e32 v22, 0
	v_mov_b32_e32 v23, 0
	v_mov_b32_e32 v24, 0
	v_mov_b32_e32 v25, 0
	v_mov_b32_e32 v26, 0
	v_mov_b32_e32 v27, 0
	v_mov_b32_e32 v28, 0
	v_mov_b32_e32 v29, 0
	v_mov_b32_e32 v30, 0
	v_mov_b32_e32 v31, 0
	v_mov_b32_e32 v32, 0
	v_mov_b32_e32 v33, 0
	v_mov_b32_e32 v2, 0
	v_mov_b32_e32 v3, 0
	v_mov_b32_e32 v4, 0
	v_mov_b32_e32 v5, 0
	v_mov_b32_e32 v6, 0
	v_mov_b32_e32 v7, 0
	v_mov_b32_e32 v8, 0
	v_mov_b32_e32 v9, 0
	v_mov_b32_e32 v10, 0
	v_mov_b32_e32 v11, 0
	v_mov_b32_e32 v12, 0
	v_mov_b32_e32 v13, 0
	v_mov_b32_e32 v14, 0
	v_mov_b32_e32 v15, 0
	v_mov_b32_e32 v16, 0
	v_mov_b32_e32 v17, 0
	s_setprio 0
	s_cmp_lt_i32 s5, s4
	s_cbranch_scc1 .LBB0_22

.LBB0_40:
	s_setprio 3
	s_mul_i32 s1, s5, s82
	s_add_i32 s1, s1, s63
	s_mul_hi_i32 s3, s1, 0x2e8ba2e9
	s_lshr_b32 s6, s3, 31
	s_ashr_i32 s3, s3, 4
	s_add_i32 s3, s3, s6
	s_mul_i32 s6, s3, 0x58
	s_sub_i32 s1, s1, s6
	s_lshl_b32 s3, s3, 1
	s_and_b32 s6, s1, 1
	s_or_b32 s3, s6, s3
	v_readlane_b32 s6, v252, 35
	s_sub_i32 s8, 0x7f, s3
	v_readlane_b32 s7, v252, 36
	s_and_b64 s[6:7], s[6:7], exec
	s_cselect_b32 s6, s8, s3
	v_mov_b32_e32 v0, v222
	s_ashr_i32 s7, s6, 31
	v_and_b32_e32 v192, 0xffffff80, v0
	s_lshl_b64 s[6:7], s[6:7], 8
	v_ashrrev_i32_e32 v193, 31, v192
	s_lshl_b32 s1, s1, 6
	v_lshl_add_u64 v[192:193], s[6:7], 0, v[192:193]
	v_readlane_b32 s6, v252, 45
	s_and_b32 s1, s1, 0xffffff80
	v_readlane_b32 s7, v252, 46
	v_and_or_b32 v185, v0, 64, s1
	v_lshrrev_b32_e32 v190, 3, v0
	v_and_or_b32 v0, v0, 31, v192
	v_mov_b64_e32 v[194:195], s[6:7]
	s_movk_i32 s1, 0x1600
	v_mad_u64_u32 v[194:195], s[6:7], v0, s1, v[194:195]
	v_mul_f32_e32 v0, 0xbfb8aa3b, v114
	v_exp_f32_e32 v0, v0
	v_mad_i32_i24 v195, v193, s1, v195
	v_ashrrev_i32_e32 v185, 1, v185
	v_and_or_b32 v190, v190, 4, v185
	v_add_f32_e32 v0, 1.0, v0
	v_rcp_f32_e32 v192, v0
	v_mul_f32_e32 v0, 0xbfb8aa3b, v115
	v_exp_f32_e32 v0, v0
	v_ashrrev_i32_e32 v191, 31, v190
	v_lshl_add_u64 v[190:191], v[190:191], 1, v[194:195]
	s_mov_b32 s1, 0x2c000
	v_add_f32_e32 v0, 1.0, v0
	v_rcp_f32_e32 v193, v0
	v_mul_f32_e32 v0, 0xbfb8aa3b, v116
	v_exp_f32_e32 v0, v0
	s_mov_b64 s[6:7], 0x2c000
	v_pk_mul_f32 v[114:115], v[114:115], v[192:193]
	s_mov_b32 s3, 0
	v_add_f32_e32 v0, 1.0, v0
	v_pk_mul_f32 v[98:99], v[98:99], v[114:115]
	v_rcp_f32_e32 v114, v0
	v_mul_f32_e32 v0, 0xbfb8aa3b, v117
	v_exp_f32_e32 v0, v0
	v_cvt_pk_bf16_f32 v98, v98, v99
	s_add_i32 s5, s5, 1
	v_add_f32_e32 v0, 1.0, v0
	v_rcp_f32_e32 v115, v0
	v_mul_f32_e32 v0, 0xbfb8aa3b, v118
	v_exp_f32_e32 v0, v0
	v_pk_mul_f32 v[114:115], v[116:117], v[114:115]
	s_nop 0
	v_pk_mul_f32 v[100:101], v[100:101], v[114:115]
	v_add_f32_e32 v0, 1.0, v0
	v_cvt_pk_bf16_f32 v99, v100, v101
	global_store_dwordx2 v[190:191], v[98:99], off
	v_rcp_f32_e32 v98, v0
	v_mul_f32_e32 v0, 0xbfb8aa3b, v119
	v_exp_f32_e32 v0, v0
	v_mov_b32_e32 v114, 0
	v_mov_b32_e32 v115, v114
	v_mov_b32_e32 v116, v114
	v_add_f32_e32 v0, 1.0, v0
	v_rcp_f32_e32 v99, v0
	v_mul_f32_e32 v0, 0xbfb8aa3b, v120
	v_exp_f32_e32 v0, v0
	v_mov_b32_e32 v117, v114
	v_pk_mul_f32 v[98:99], v[118:119], v[98:99]
	v_mov_b32_e32 v118, v114
	v_add_f32_e32 v0, 1.0, v0
	v_rcp_f32_e32 v100, v0
	v_mul_f32_e32 v0, 0xbfb8aa3b, v121
	v_exp_f32_e32 v0, v0
	v_pk_mul_f32 v[98:99], v[102:103], v[98:99]
	v_mov_b32_e32 v119, v114
	v_cvt_pk_bf16_f32 v98, v98, v99
	v_add_f32_e32 v0, 1.0, v0
	v_rcp_f32_e32 v101, v0
	v_mul_f32_e32 v0, 0xbfb8aa3b, v122
	v_exp_f32_e32 v0, v0
	v_mov_b32_e32 v102, v114
	v_pk_mul_f32 v[100:101], v[120:121], v[100:101]
	v_mov_b32_e32 v120, v114
	v_pk_mul_f32 v[100:101], v[104:105], v[100:101]
	v_add_f32_e32 v0, 1.0, v0
	v_cvt_pk_bf16_f32 v99, v100, v101
	global_store_dwordx2 v[190:191], v[98:99], off offset:16
	v_rcp_f32_e32 v98, v0
	v_mul_f32_e32 v0, 0xbfb8aa3b, v123
	v_exp_f32_e32 v0, v0
	v_mov_b32_e32 v121, v114
	v_mov_b32_e32 v103, v114
	v_mov_b32_e32 v104, v114
	v_add_f32_e32 v0, 1.0, v0
	v_rcp_f32_e32 v99, v0
	v_mul_f32_e32 v0, 0xbfb8aa3b, v124
	v_exp_f32_e32 v0, v0
	v_mov_b32_e32 v105, v114
	v_pk_mul_f32 v[98:99], v[122:123], v[98:99]
	v_mov_b32_e32 v122, v114
	v_add_f32_e32 v0, 1.0, v0
	v_rcp_f32_e32 v100, v0
	v_mul_f32_e32 v0, 0xbfb8aa3b, v125
	v_exp_f32_e32 v0, v0
	v_pk_mul_f32 v[98:99], v[106:107], v[98:99]
	v_mov_b32_e32 v123, v114
	v_cvt_pk_bf16_f32 v98, v98, v99
	v_add_f32_e32 v0, 1.0, v0
	v_rcp_f32_e32 v101, v0
	v_mul_f32_e32 v0, 0xbfb8aa3b, v126
	v_exp_f32_e32 v0, v0
	v_mov_b32_e32 v106, v114
	v_pk_mul_f32 v[100:101], v[124:125], v[100:101]
	v_mov_b32_e32 v124, v114
	v_pk_mul_f32 v[100:101], v[108:109], v[100:101]
	v_add_f32_e32 v0, 1.0, v0
	v_cvt_pk_bf16_f32 v99, v100, v101
	global_store_dwordx2 v[190:191], v[98:99], off offset:32
	v_rcp_f32_e32 v98, v0
	v_mul_f32_e32 v0, 0xbfb8aa3b, v127
	v_exp_f32_e32 v0, v0
	v_mov_b32_e32 v125, v114
	v_mov_b32_e32 v107, v114
	v_mov_b32_e32 v108, v114
	v_add_f32_e32 v0, 1.0, v0
	v_rcp_f32_e32 v99, v0
	v_mul_f32_e32 v0, 0xbfb8aa3b, v128
	v_exp_f32_e32 v0, v0
	v_mov_b32_e32 v109, v114
	v_pk_mul_f32 v[98:99], v[126:127], v[98:99]
	v_mov_b32_e32 v126, v114
	v_add_f32_e32 v0, 1.0, v0
	v_rcp_f32_e32 v100, v0
	v_mul_f32_e32 v0, 0xbfb8aa3b, v129
	v_exp_f32_e32 v0, v0
	v_pk_mul_f32 v[98:99], v[110:111], v[98:99]
	v_mov_b32_e32 v127, v114
	v_cvt_pk_bf16_f32 v98, v98, v99
	v_add_f32_e32 v0, 1.0, v0
	v_rcp_f32_e32 v101, v0
	v_mul_f32_e32 v0, 0xbfb8aa3b, v82
	v_exp_f32_e32 v0, v0
	v_mov_b32_e32 v110, v114
	v_pk_mul_f32 v[100:101], v[128:129], v[100:101]
	v_mov_b32_e32 v128, v114
	v_pk_mul_f32 v[100:101], v[112:113], v[100:101]
	v_add_f32_e32 v0, 1.0, v0
	v_cvt_pk_bf16_f32 v99, v100, v101
	v_rcp_f32_e32 v100, v0
	v_mul_f32_e32 v0, 0xbfb8aa3b, v83
	v_exp_f32_e32 v0, v0
	global_store_dwordx2 v[190:191], v[98:99], off offset:48
	v_lshl_add_u64 v[98:99], v[190:191], 0, s[6:7]
	s_mov_b64 s[6:7], 0x58000
	v_add_f32_e32 v0, 1.0, v0
	v_rcp_f32_e32 v101, v0
	v_mul_f32_e32 v0, 0xbfb8aa3b, v84
	v_exp_f32_e32 v0, v0
	v_mov_b32_e32 v129, v114
	v_pk_mul_f32 v[82:83], v[82:83], v[100:101]
	v_mov_b32_e32 v100, v114
	v_add_f32_e32 v0, 1.0, v0
	v_pk_mul_f32 v[66:67], v[66:67], v[82:83]
	v_rcp_f32_e32 v82, v0
	v_mul_f32_e32 v0, 0xbfb8aa3b, v85
	v_exp_f32_e32 v0, v0
	v_cvt_pk_bf16_f32 v66, v66, v67
	v_mov_b32_e32 v101, v114
	v_mov_b32_e32 v111, v114
	v_add_f32_e32 v0, 1.0, v0
	v_rcp_f32_e32 v83, v0
	v_mul_f32_e32 v0, 0xbfb8aa3b, v86
	v_exp_f32_e32 v0, v0
	v_mov_b32_e32 v112, v114
	v_pk_mul_f32 v[82:83], v[84:85], v[82:83]
	v_mov_b32_e32 v113, v114
	v_pk_mul_f32 v[68:69], v[68:69], v[82:83]
	v_add_f32_e32 v0, 1.0, v0
	v_cvt_pk_bf16_f32 v67, v68, v69
	v_add_co_u32_e32 v68, vcc, s1, v190
	s_mov_b32 s1, 0x58000
	s_nop 0
	v_addc_co_u32_e32 v69, vcc, 0, v191, vcc
	global_store_dwordx2 v[68:69], v[66:67], off
	v_rcp_f32_e32 v66, v0
	v_mul_f32_e32 v0, 0xbfb8aa3b, v87
	v_exp_f32_e32 v0, v0
	v_mov_b32_e32 v82, v114
	v_mov_b32_e32 v83, v114
	v_mov_b32_e32 v84, v114
	v_add_f32_e32 v0, 1.0, v0
	v_rcp_f32_e32 v67, v0
	v_mul_f32_e32 v0, 0xbfb8aa3b, v88
	v_exp_f32_e32 v0, v0
	v_mov_b32_e32 v85, v114
	v_pk_mul_f32 v[66:67], v[86:87], v[66:67]
	v_mov_b32_e32 v86, v114
	v_add_f32_e32 v0, 1.0, v0
	v_rcp_f32_e32 v68, v0
	v_mul_f32_e32 v0, 0xbfb8aa3b, v89
	v_exp_f32_e32 v0, v0
	v_pk_mul_f32 v[66:67], v[70:71], v[66:67]
	v_mov_b32_e32 v87, v114
	v_cvt_pk_bf16_f32 v66, v66, v67
	v_add_f32_e32 v0, 1.0, v0
	v_rcp_f32_e32 v69, v0
	v_mul_f32_e32 v0, 0xbfb8aa3b, v90
	v_exp_f32_e32 v0, v0
	v_mov_b32_e32 v70, v114
	v_pk_mul_f32 v[68:69], v[88:89], v[68:69]
	v_mov_b32_e32 v88, v114
	v_pk_mul_f32 v[68:69], v[72:73], v[68:69]
	v_add_f32_e32 v0, 1.0, v0
	v_cvt_pk_bf16_f32 v67, v68, v69
	global_store_dwordx2 v[98:99], v[66:67], off offset:16
	v_rcp_f32_e32 v66, v0
	v_mul_f32_e32 v0, 0xbfb8aa3b, v91
	v_exp_f32_e32 v0, v0
	v_mov_b32_e32 v89, v114
	v_mov_b32_e32 v71, v114
	v_mov_b32_e32 v72, v114
	v_add_f32_e32 v0, 1.0, v0
	v_rcp_f32_e32 v67, v0
	v_mul_f32_e32 v0, 0xbfb8aa3b, v92
	v_exp_f32_e32 v0, v0
	v_mov_b32_e32 v73, v114
	v_pk_mul_f32 v[66:67], v[90:91], v[66:67]
	v_mov_b32_e32 v90, v114
	v_add_f32_e32 v0, 1.0, v0
	v_rcp_f32_e32 v68, v0
	v_mul_f32_e32 v0, 0xbfb8aa3b, v93
	v_exp_f32_e32 v0, v0
	v_pk_mul_f32 v[66:67], v[74:75], v[66:67]
	v_mov_b32_e32 v91, v114
	v_cvt_pk_bf16_f32 v66, v66, v67
	v_add_f32_e32 v0, 1.0, v0
	v_rcp_f32_e32 v69, v0
	v_mul_f32_e32 v0, 0xbfb8aa3b, v94
	v_exp_f32_e32 v0, v0
	v_mov_b32_e32 v74, v114
	v_pk_mul_f32 v[68:69], v[92:93], v[68:69]
	v_mov_b32_e32 v92, v114
	v_pk_mul_f32 v[68:69], v[76:77], v[68:69]
	v_add_f32_e32 v0, 1.0, v0
	v_cvt_pk_bf16_f32 v67, v68, v69
	global_store_dwordx2 v[98:99], v[66:67], off offset:32
	v_rcp_f32_e32 v66, v0
	v_mul_f32_e32 v0, 0xbfb8aa3b, v95
	v_exp_f32_e32 v0, v0
	v_mov_b32_e32 v93, v114
	v_mov_b32_e32 v75, v114
	v_mov_b32_e32 v76, v114
	v_add_f32_e32 v0, 1.0, v0
	v_rcp_f32_e32 v67, v0
	v_mul_f32_e32 v0, 0xbfb8aa3b, v96
	v_exp_f32_e32 v0, v0
	v_mov_b32_e32 v77, v114
	v_pk_mul_f32 v[66:67], v[94:95], v[66:67]
	v_mov_b32_e32 v94, v114
	v_add_f32_e32 v0, 1.0, v0
	v_rcp_f32_e32 v68, v0
	v_mul_f32_e32 v0, 0xbfb8aa3b, v97
	v_exp_f32_e32 v0, v0
	v_pk_mul_f32 v[66:67], v[78:79], v[66:67]
	v_mov_b32_e32 v95, v114
	v_cvt_pk_bf16_f32 v66, v66, v67
	v_add_f32_e32 v0, 1.0, v0
	v_rcp_f32_e32 v69, v0
	v_mul_f32_e32 v0, 0xbfb8aa3b, v50
	v_exp_f32_e32 v0, v0
	v_mov_b32_e32 v78, v114
	v_pk_mul_f32 v[68:69], v[96:97], v[68:69]
	v_mov_b32_e32 v96, v114
	v_pk_mul_f32 v[68:69], v[80:81], v[68:69]
	v_add_f32_e32 v0, 1.0, v0
	v_cvt_pk_bf16_f32 v67, v68, v69
	v_rcp_f32_e32 v68, v0
	v_mul_f32_e32 v0, 0xbfb8aa3b, v51
	v_exp_f32_e32 v0, v0
	global_store_dwordx2 v[98:99], v[66:67], off offset:48
	v_lshl_add_u64 v[66:67], v[190:191], 0, s[6:7]
	s_mov_b64 s[6:7], 0x84000
	v_add_f32_e32 v0, 1.0, v0
	v_rcp_f32_e32 v69, v0
	v_mul_f32_e32 v0, 0xbfb8aa3b, v52
	v_exp_f32_e32 v0, v0
	v_mov_b32_e32 v98, v114
	v_pk_mul_f32 v[50:51], v[50:51], v[68:69]
	v_mov_b32_e32 v99, v114
	v_add_f32_e32 v0, 1.0, v0
	v_pk_mul_f32 v[34:35], v[34:35], v[50:51]
	v_rcp_f32_e32 v50, v0
	v_mul_f32_e32 v0, 0xbfb8aa3b, v53
	v_exp_f32_e32 v0, v0
	v_cvt_pk_bf16_f32 v34, v34, v35
	v_mov_b32_e32 v97, v114
	v_mov_b32_e32 v68, v114
	v_add_f32_e32 v0, 1.0, v0
	v_rcp_f32_e32 v51, v0
	v_mul_f32_e32 v0, 0xbfb8aa3b, v54
	v_exp_f32_e32 v0, v0
	v_mov_b32_e32 v69, v114
	v_pk_mul_f32 v[50:51], v[52:53], v[50:51]
	v_mov_b32_e32 v79, v114
	v_pk_mul_f32 v[36:37], v[36:37], v[50:51]
	v_add_f32_e32 v0, 1.0, v0
	v_cvt_pk_bf16_f32 v35, v36, v37
	v_add_co_u32_e32 v36, vcc, s1, v190
	s_mov_b32 s1, 0x84000
	s_nop 0
	v_addc_co_u32_e32 v37, vcc, 0, v191, vcc
	global_store_dwordx2 v[36:37], v[34:35], off
	v_rcp_f32_e32 v34, v0
	v_mul_f32_e32 v0, 0xbfb8aa3b, v55
	v_exp_f32_e32 v0, v0
	v_mov_b32_e32 v80, v114
	v_mov_b32_e32 v81, v114
	v_mov_b32_e32 v50, v114
	v_add_f32_e32 v0, 1.0, v0
	v_rcp_f32_e32 v35, v0
	v_mul_f32_e32 v0, 0xbfb8aa3b, v56
	v_exp_f32_e32 v0, v0
	v_mov_b32_e32 v51, v114
	v_pk_mul_f32 v[34:35], v[54:55], v[34:35]
	v_mov_b32_e32 v52, v114
	v_add_f32_e32 v0, 1.0, v0
	v_rcp_f32_e32 v36, v0
	v_mul_f32_e32 v0, 0xbfb8aa3b, v57
	v_exp_f32_e32 v0, v0
	v_pk_mul_f32 v[34:35], v[38:39], v[34:35]
	v_mov_b32_e32 v53, v114
	v_cvt_pk_bf16_f32 v34, v34, v35
	v_add_f32_e32 v0, 1.0, v0
	v_rcp_f32_e32 v37, v0
	v_mul_f32_e32 v0, 0xbfb8aa3b, v58
	v_exp_f32_e32 v0, v0
	v_mov_b32_e32 v54, v114
	v_pk_mul_f32 v[36:37], v[56:57], v[36:37]
	v_mov_b32_e32 v55, v114
	v_pk_mul_f32 v[36:37], v[40:41], v[36:37]
	v_add_f32_e32 v0, 1.0, v0
	v_cvt_pk_bf16_f32 v35, v36, v37
	global_store_dwordx2 v[66:67], v[34:35], off offset:16
	v_rcp_f32_e32 v34, v0
	v_mul_f32_e32 v0, 0xbfb8aa3b, v59
	v_exp_f32_e32 v0, v0
	v_mov_b32_e32 v56, v114
	v_mov_b32_e32 v57, v114
	v_mov_b32_e32 v38, v114
	v_add_f32_e32 v0, 1.0, v0
	v_rcp_f32_e32 v35, v0
	v_mul_f32_e32 v0, 0xbfb8aa3b, v60
	v_exp_f32_e32 v0, v0
	v_mov_b32_e32 v39, v114
	v_pk_mul_f32 v[34:35], v[58:59], v[34:35]
	v_mov_b32_e32 v58, v114
	v_add_f32_e32 v0, 1.0, v0
	v_rcp_f32_e32 v36, v0
	v_mul_f32_e32 v0, 0xbfb8aa3b, v61
	v_exp_f32_e32 v0, v0
	v_pk_mul_f32 v[34:35], v[42:43], v[34:35]
	v_mov_b32_e32 v59, v114
	v_cvt_pk_bf16_f32 v34, v34, v35
	v_add_f32_e32 v0, 1.0, v0
	v_rcp_f32_e32 v37, v0
	v_mul_f32_e32 v0, 0xbfb8aa3b, v62
	v_exp_f32_e32 v0, v0
	v_mov_b32_e32 v40, v114
	v_pk_mul_f32 v[36:37], v[60:61], v[36:37]
	v_mov_b32_e32 v60, v114
	v_pk_mul_f32 v[36:37], v[44:45], v[36:37]
	v_add_f32_e32 v0, 1.0, v0
	v_cvt_pk_bf16_f32 v35, v36, v37
	global_store_dwordx2 v[66:67], v[34:35], off offset:32
	v_rcp_f32_e32 v34, v0
	v_mul_f32_e32 v0, 0xbfb8aa3b, v63
	v_exp_f32_e32 v0, v0
	v_mov_b32_e32 v61, v114
	v_mov_b32_e32 v41, v114
	v_mov_b32_e32 v42, v114
	v_add_f32_e32 v0, 1.0, v0
	v_rcp_f32_e32 v35, v0
	v_mul_f32_e32 v0, 0xbfb8aa3b, v64
	v_exp_f32_e32 v0, v0
	v_mov_b32_e32 v43, v114
	v_pk_mul_f32 v[34:35], v[62:63], v[34:35]
	v_mov_b32_e32 v62, v114
	v_add_f32_e32 v0, 1.0, v0
	v_rcp_f32_e32 v36, v0
	v_mul_f32_e32 v0, 0xbfb8aa3b, v65
	v_exp_f32_e32 v0, v0
	v_pk_mul_f32 v[34:35], v[46:47], v[34:35]
	v_mov_b32_e32 v63, v114
	v_cvt_pk_bf16_f32 v34, v34, v35
	v_add_f32_e32 v0, 1.0, v0
	v_rcp_f32_e32 v37, v0
	v_mul_f32_e32 v0, 0xbfb8aa3b, v18
	v_exp_f32_e32 v0, v0
	v_mov_b32_e32 v44, v114
	v_pk_mul_f32 v[36:37], v[64:65], v[36:37]
	v_mov_b32_e32 v64, v114
	v_pk_mul_f32 v[36:37], v[48:49], v[36:37]
	v_add_f32_e32 v0, 1.0, v0
	v_cvt_pk_bf16_f32 v35, v36, v37
	v_rcp_f32_e32 v36, v0
	v_mul_f32_e32 v0, 0xbfb8aa3b, v19
	v_exp_f32_e32 v0, v0
	global_store_dwordx2 v[66:67], v[34:35], off offset:48
	v_lshl_add_u64 v[34:35], v[190:191], 0, s[6:7]
	v_mov_b32_e32 v66, v114
	v_add_f32_e32 v0, 1.0, v0
	v_rcp_f32_e32 v37, v0
	v_mul_f32_e32 v0, 0xbfb8aa3b, v20
	v_exp_f32_e32 v0, v0
	v_mov_b32_e32 v67, v114
	v_pk_mul_f32 v[18:19], v[18:19], v[36:37]
	v_mov_b32_e32 v65, v114
	v_add_f32_e32 v0, 1.0, v0
	v_pk_mul_f32 v[2:3], v[2:3], v[18:19]
	v_rcp_f32_e32 v18, v0
	v_mul_f32_e32 v0, 0xbfb8aa3b, v21
	v_exp_f32_e32 v0, v0
	v_cvt_pk_bf16_f32 v2, v2, v3
	v_mov_b32_e32 v36, v114
	v_mov_b32_e32 v37, v114
	v_add_f32_e32 v0, 1.0, v0
	v_rcp_f32_e32 v19, v0
	v_mul_f32_e32 v0, 0xbfb8aa3b, v22
	v_exp_f32_e32 v0, v0
	v_mov_b32_e32 v45, v114
	v_pk_mul_f32 v[18:19], v[20:21], v[18:19]
	v_mov_b32_e32 v46, v114
	v_pk_mul_f32 v[4:5], v[4:5], v[18:19]
	v_add_f32_e32 v0, 1.0, v0
	v_cvt_pk_bf16_f32 v3, v4, v5
	v_add_co_u32_e32 v4, vcc, s1, v190
	v_mov_b32_e32 v47, v114
	s_nop 0
	v_addc_co_u32_e32 v5, vcc, 0, v191, vcc
	global_store_dwordx2 v[4:5], v[2:3], off
	v_rcp_f32_e32 v2, v0
	v_mul_f32_e32 v0, 0xbfb8aa3b, v23
	v_exp_f32_e32 v0, v0
	v_mov_b32_e32 v48, v114
	v_mov_b32_e32 v49, v114
	v_mov_b32_e32 v18, v114
	v_add_f32_e32 v0, 1.0, v0
	v_rcp_f32_e32 v3, v0
	v_mul_f32_e32 v0, 0xbfb8aa3b, v24
	v_exp_f32_e32 v0, v0
	v_mov_b32_e32 v19, v114
	v_pk_mul_f32 v[2:3], v[22:23], v[2:3]
	v_mov_b32_e32 v20, v114
	v_add_f32_e32 v0, 1.0, v0
	v_rcp_f32_e32 v4, v0
	v_mul_f32_e32 v0, 0xbfb8aa3b, v25
	v_exp_f32_e32 v0, v0
	v_pk_mul_f32 v[2:3], v[6:7], v[2:3]
	v_mov_b32_e32 v21, v114
	v_cvt_pk_bf16_f32 v2, v2, v3
	v_add_f32_e32 v0, 1.0, v0
	v_rcp_f32_e32 v5, v0
	v_mul_f32_e32 v0, 0xbfb8aa3b, v26
	v_exp_f32_e32 v0, v0
	v_mov_b32_e32 v22, v114
	v_pk_mul_f32 v[4:5], v[24:25], v[4:5]
	v_mov_b32_e32 v23, v114
	v_pk_mul_f32 v[4:5], v[8:9], v[4:5]
	v_add_f32_e32 v0, 1.0, v0
	v_cvt_pk_bf16_f32 v3, v4, v5
	global_store_dwordx2 v[34:35], v[2:3], off offset:16
	v_rcp_f32_e32 v2, v0
	v_mul_f32_e32 v0, 0xbfb8aa3b, v27
	v_exp_f32_e32 v0, v0
	v_mov_b32_e32 v24, v114
	v_mov_b32_e32 v25, v114
	v_mov_b32_e32 v6, v114
	v_add_f32_e32 v0, 1.0, v0
	v_rcp_f32_e32 v3, v0
	v_mul_f32_e32 v0, 0xbfb8aa3b, v28
	v_exp_f32_e32 v0, v0
	v_mov_b32_e32 v7, v114
	v_pk_mul_f32 v[2:3], v[26:27], v[2:3]
	v_mov_b32_e32 v26, v114
	v_add_f32_e32 v0, 1.0, v0
	v_rcp_f32_e32 v4, v0
	v_mul_f32_e32 v0, 0xbfb8aa3b, v29
	v_exp_f32_e32 v0, v0
	v_pk_mul_f32 v[2:3], v[10:11], v[2:3]
	v_mov_b32_e32 v27, v114
	v_cvt_pk_bf16_f32 v2, v2, v3
	v_add_f32_e32 v0, 1.0, v0
	v_rcp_f32_e32 v5, v0
	v_mul_f32_e32 v0, 0xbfb8aa3b, v30
	v_exp_f32_e32 v0, v0
	v_mov_b32_e32 v8, v114
	v_pk_mul_f32 v[4:5], v[28:29], v[4:5]
	v_mov_b32_e32 v28, v114
	v_pk_mul_f32 v[4:5], v[12:13], v[4:5]
	v_add_f32_e32 v0, 1.0, v0
	v_cvt_pk_bf16_f32 v3, v4, v5
	global_store_dwordx2 v[34:35], v[2:3], off offset:32
	v_rcp_f32_e32 v2, v0
	v_mul_f32_e32 v0, 0xbfb8aa3b, v31
	v_exp_f32_e32 v0, v0
	v_mov_b32_e32 v29, v114
	v_mov_b32_e32 v9, v114
	v_mov_b32_e32 v10, v114
	v_add_f32_e32 v0, 1.0, v0
	v_rcp_f32_e32 v3, v0
	v_mul_f32_e32 v0, 0xbfb8aa3b, v32
	v_exp_f32_e32 v0, v0
	v_mov_b32_e32 v11, v114
	v_pk_mul_f32 v[2:3], v[30:31], v[2:3]
	v_mov_b32_e32 v30, v114
	v_add_f32_e32 v0, 1.0, v0
	v_rcp_f32_e32 v4, v0
	v_mul_f32_e32 v0, 0xbfb8aa3b, v33
	v_exp_f32_e32 v0, v0
	v_pk_mul_f32 v[2:3], v[14:15], v[2:3]
	v_mov_b32_e32 v31, v114
	v_cvt_pk_bf16_f32 v2, v2, v3
	v_add_f32_e32 v0, 1.0, v0
	v_rcp_f32_e32 v5, v0
	v_mov_b32_e32 v12, v114
	v_mov_b32_e32 v13, v114
	v_mov_b32_e32 v14, v114
	v_pk_mul_f32 v[4:5], v[32:33], v[4:5]
	v_mov_b32_e32 v32, v114
	v_pk_mul_f32 v[4:5], v[16:17], v[4:5]
	v_mov_b32_e32 v33, v114
	v_cvt_pk_bf16_f32 v3, v4, v5
	global_store_dwordx2 v[34:35], v[2:3], off offset:48
	v_mov_b32_e32 v34, v114
	v_mov_b32_e32 v35, v114
	v_mov_b32_e32 v2, v114
	v_mov_b32_e32 v3, v114
	v_mov_b32_e32 v4, v114
	v_mov_b32_e32 v5, v114
	v_mov_b32_e32 v15, v114
	v_mov_b32_e32 v16, v114
	v_mov_b32_e32 v17, v114
	s_setprio 0
	s_cmp_ge_i32 s5, s4
	s_cbranch_scc0 .LBB0_36

.LBB0_68:
	s_setprio 3
	s_mul_i32 s1, s7, s82
	s_add_i32 s1, s1, s63
	s_ashr_i32 s3, s1, 31
	s_lshr_b32 s3, s3, 28
	s_add_i32 s3, s1, s3
	s_ashr_i32 s4, s3, 4
	s_and_b32 s3, s3, -16
	s_sub_i32 s1, s1, s3
	s_lshl_b32 s3, s4, 1
	s_and_b32 s4, s1, 1
	s_or_b32 s3, s4, s3
	v_readlane_b32 s4, v252, 35
	s_sub_i32 s8, 0x7f, s3
	v_readlane_b32 s5, v252, 36
	s_and_b64 s[4:5], s[4:5], exec
	s_cselect_b32 s4, s8, s3
	v_mov_b32_e32 v0, v222
	s_ashr_i32 s5, s4, 31
	v_and_b32_e32 v190, 0xffffff80, v0
	s_lshl_b64 s[4:5], s[4:5], 8
	v_ashrrev_i32_e32 v191, 31, v190
	v_lshl_add_u64 v[190:191], s[4:5], 0, v[190:191]
	s_lshl_b32 s1, s1, 6
	v_and_b32_e32 v185, 64, v0
	v_and_or_b32 v190, v0, 31, v190
	s_and_b32 s1, s1, 0xffffff80
	v_lshrrev_b32_e32 v0, 3, v0
	v_readlane_b32 s4, v252, 31
	s_ashr_i32 s3, s1, 31
	v_and_b32_e32 v0, 4, v0
	v_lshlrev_b64 v[190:191], 12, v[190:191]
	v_readlane_b32 s5, v252, 32
	v_or3_b32 v192, v0, v185, s1
	v_mov_b32_e32 v193, s3
	v_lshl_add_u64 v[190:191], s[4:5], 0, v[190:191]
	v_lshl_add_u64 v[190:191], v[192:193], 2, v[190:191]
	s_mov_b64 s[98:99], 0x20000
	v_lshl_add_u64 v[192:193], v[190:191], 0, 0
	v_lshl_add_u64 v[220:221], v[190:191], 0, 0
	global_load_dwordx4 v[194:197], v[192:193], off
	global_load_dwordx4 v[198:201], v[192:193], off offset:32
	global_load_dwordx4 v[202:205], v[192:193], off offset:64
	global_load_dwordx4 v[206:209], v[192:193], off offset:96
	global_load_dwordx4 v[216:219], v[192:193], off offset:128
	global_load_dwordx4 v[236:239], v[192:193], off offset:160
	global_load_dwordx4 v[240:243], v[192:193], off offset:192
	global_load_dwordx4 v[244:247], v[192:193], off offset:224
	s_waitcnt vmcnt(7)
	v_pk_add_f32 v[114:115], v[114:115], v[194:195]
	v_pk_add_f32 v[116:117], v[116:117], v[196:197]
	global_store_dwordx4 v[220:221], v[114:117], off
	v_lshl_add_u64 v[192:193], v[192:193], 0, s[98:99]
	global_load_dwordx4 v[194:197], v[192:193], off
	s_waitcnt vmcnt(8)
	v_pk_add_f32 v[118:119], v[118:119], v[198:199]
	v_pk_add_f32 v[120:121], v[120:121], v[200:201]
	global_store_dwordx4 v[220:221], v[118:121], off offset:32
	global_load_dwordx4 v[198:201], v[192:193], off offset:32
	s_waitcnt vmcnt(9)
	v_pk_add_f32 v[122:123], v[122:123], v[202:203]
	v_pk_add_f32 v[124:125], v[124:125], v[204:205]
	global_store_dwordx4 v[220:221], v[122:125], off offset:64
	global_load_dwordx4 v[202:205], v[192:193], off offset:64
	s_waitcnt vmcnt(10)
	v_pk_add_f32 v[126:127], v[126:127], v[206:207]
	v_pk_add_f32 v[128:129], v[128:129], v[208:209]
	global_store_dwordx4 v[220:221], v[126:129], off offset:96
	global_load_dwordx4 v[206:209], v[192:193], off offset:96
	s_waitcnt vmcnt(11)
	v_pk_add_f32 v[98:99], v[98:99], v[216:217]
	v_pk_add_f32 v[100:101], v[100:101], v[218:219]
	global_store_dwordx4 v[220:221], v[98:101], off offset:128
	global_load_dwordx4 v[216:219], v[192:193], off offset:128
	s_waitcnt vmcnt(12)
	v_pk_add_f32 v[102:103], v[102:103], v[236:237]
	v_pk_add_f32 v[104:105], v[104:105], v[238:239]
	global_store_dwordx4 v[220:221], v[102:105], off offset:160
	global_load_dwordx4 v[236:239], v[192:193], off offset:160
	s_waitcnt vmcnt(13)
	v_pk_add_f32 v[106:107], v[106:107], v[240:241]
	v_pk_add_f32 v[108:109], v[108:109], v[242:243]
	global_store_dwordx4 v[220:221], v[106:109], off offset:192
	global_load_dwordx4 v[240:243], v[192:193], off offset:192
	s_waitcnt vmcnt(14)
	v_pk_add_f32 v[110:111], v[110:111], v[244:245]
	v_pk_add_f32 v[112:113], v[112:113], v[246:247]
	global_store_dwordx4 v[220:221], v[110:113], off offset:224
	global_load_dwordx4 v[244:247], v[192:193], off offset:224
	s_waitcnt vmcnt(14)
	v_pk_add_f32 v[82:83], v[82:83], v[194:195]
	v_pk_add_f32 v[84:85], v[84:85], v[196:197]
	v_lshl_add_u64 v[220:221], v[220:221], 0, s[98:99]
	global_store_dwordx4 v[220:221], v[82:85], off
	v_lshl_add_u64 v[192:193], v[192:193], 0, s[98:99]
	global_load_dwordx4 v[194:197], v[192:193], off
	s_waitcnt vmcnt(14)
	v_pk_add_f32 v[86:87], v[86:87], v[198:199]
	v_pk_add_f32 v[88:89], v[88:89], v[200:201]
	global_store_dwordx4 v[220:221], v[86:89], off offset:32
	global_load_dwordx4 v[198:201], v[192:193], off offset:32
	s_waitcnt vmcnt(14)
	v_pk_add_f32 v[90:91], v[90:91], v[202:203]
	v_pk_add_f32 v[92:93], v[92:93], v[204:205]
	global_store_dwordx4 v[220:221], v[90:93], off offset:64
	global_load_dwordx4 v[202:205], v[192:193], off offset:64
	s_waitcnt vmcnt(14)
	v_pk_add_f32 v[94:95], v[94:95], v[206:207]
	v_pk_add_f32 v[96:97], v[96:97], v[208:209]
	global_store_dwordx4 v[220:221], v[94:97], off offset:96
	global_load_dwordx4 v[206:209], v[192:193], off offset:96
	s_waitcnt vmcnt(14)
	v_pk_add_f32 v[66:67], v[66:67], v[216:217]
	v_pk_add_f32 v[68:69], v[68:69], v[218:219]
	global_store_dwordx4 v[220:221], v[66:69], off offset:128
	global_load_dwordx4 v[216:219], v[192:193], off offset:128
	s_waitcnt vmcnt(14)
	v_pk_add_f32 v[70:71], v[70:71], v[236:237]
	v_pk_add_f32 v[72:73], v[72:73], v[238:239]
	global_store_dwordx4 v[220:221], v[70:73], off offset:160
	global_load_dwordx4 v[236:239], v[192:193], off offset:160
	s_waitcnt vmcnt(14)
	v_pk_add_f32 v[74:75], v[74:75], v[240:241]
	v_pk_add_f32 v[76:77], v[76:77], v[242:243]
	global_store_dwordx4 v[220:221], v[74:77], off offset:192
	global_load_dwordx4 v[240:243], v[192:193], off offset:192
	s_waitcnt vmcnt(14)
	v_pk_add_f32 v[78:79], v[78:79], v[244:245]
	v_pk_add_f32 v[80:81], v[80:81], v[246:247]
	global_store_dwordx4 v[220:221], v[78:81], off offset:224
	global_load_dwordx4 v[244:247], v[192:193], off offset:224
	s_waitcnt vmcnt(14)
	v_pk_add_f32 v[50:51], v[50:51], v[194:195]
	v_pk_add_f32 v[52:53], v[52:53], v[196:197]
	v_lshl_add_u64 v[220:221], v[220:221], 0, s[98:99]
	global_store_dwordx4 v[220:221], v[50:53], off
	v_lshl_add_u64 v[192:193], v[192:193], 0, s[98:99]
	global_load_dwordx4 v[194:197], v[192:193], off
	s_waitcnt vmcnt(14)
	v_pk_add_f32 v[54:55], v[54:55], v[198:199]
	v_pk_add_f32 v[56:57], v[56:57], v[200:201]
	global_store_dwordx4 v[220:221], v[54:57], off offset:32
	global_load_dwordx4 v[198:201], v[192:193], off offset:32
	s_waitcnt vmcnt(14)
	v_pk_add_f32 v[58:59], v[58:59], v[202:203]
	v_pk_add_f32 v[60:61], v[60:61], v[204:205]
	global_store_dwordx4 v[220:221], v[58:61], off offset:64
	global_load_dwordx4 v[202:205], v[192:193], off offset:64
	s_waitcnt vmcnt(14)
	v_pk_add_f32 v[62:63], v[62:63], v[206:207]
	v_pk_add_f32 v[64:65], v[64:65], v[208:209]
	global_store_dwordx4 v[220:221], v[62:65], off offset:96
	global_load_dwordx4 v[206:209], v[192:193], off offset:96
	s_waitcnt vmcnt(14)
	v_pk_add_f32 v[34:35], v[34:35], v[216:217]
	v_pk_add_f32 v[36:37], v[36:37], v[218:219]
	global_store_dwordx4 v[220:221], v[34:37], off offset:128
	global_load_dwordx4 v[216:219], v[192:193], off offset:128
	s_waitcnt vmcnt(14)
	v_pk_add_f32 v[38:39], v[38:39], v[236:237]
	v_pk_add_f32 v[40:41], v[40:41], v[238:239]
	global_store_dwordx4 v[220:221], v[38:41], off offset:160
	global_load_dwordx4 v[236:239], v[192:193], off offset:160
	s_waitcnt vmcnt(14)
	v_pk_add_f32 v[42:43], v[42:43], v[240:241]
	v_pk_add_f32 v[44:45], v[44:45], v[242:243]
	global_store_dwordx4 v[220:221], v[42:45], off offset:192
	global_load_dwordx4 v[240:243], v[192:193], off offset:192
	s_waitcnt vmcnt(14)
	v_pk_add_f32 v[46:47], v[46:47], v[244:245]
	v_pk_add_f32 v[48:49], v[48:49], v[246:247]
	global_store_dwordx4 v[220:221], v[46:49], off offset:224
	global_load_dwordx4 v[244:247], v[192:193], off offset:224
	s_waitcnt vmcnt(14)
	v_pk_add_f32 v[18:19], v[18:19], v[194:195]
	v_pk_add_f32 v[20:21], v[20:21], v[196:197]
	v_lshl_add_u64 v[220:221], v[220:221], 0, s[98:99]
	global_store_dwordx4 v[220:221], v[18:21], off
	s_waitcnt vmcnt(13)
	v_pk_add_f32 v[22:23], v[22:23], v[198:199]
	v_pk_add_f32 v[24:25], v[24:25], v[200:201]
	global_store_dwordx4 v[220:221], v[22:25], off offset:32
	s_waitcnt vmcnt(12)
	v_pk_add_f32 v[26:27], v[26:27], v[202:203]
	v_pk_add_f32 v[28:29], v[28:29], v[204:205]
	global_store_dwordx4 v[220:221], v[26:29], off offset:64
	s_waitcnt vmcnt(11)
	v_pk_add_f32 v[30:31], v[30:31], v[206:207]
	v_pk_add_f32 v[32:33], v[32:33], v[208:209]
	global_store_dwordx4 v[220:221], v[30:33], off offset:96
	s_waitcnt vmcnt(10)
	v_pk_add_f32 v[2:3], v[2:3], v[216:217]
	v_pk_add_f32 v[4:5], v[4:5], v[218:219]
	global_store_dwordx4 v[220:221], v[2:5], off offset:128
	s_waitcnt vmcnt(9)
	v_pk_add_f32 v[6:7], v[6:7], v[236:237]
	v_pk_add_f32 v[8:9], v[8:9], v[238:239]
	global_store_dwordx4 v[220:221], v[6:9], off offset:160
	s_waitcnt vmcnt(8)
	v_pk_add_f32 v[10:11], v[10:11], v[240:241]
	v_pk_add_f32 v[12:13], v[12:13], v[242:243]
	global_store_dwordx4 v[220:221], v[10:13], off offset:192
	s_waitcnt vmcnt(7)
	v_pk_add_f32 v[14:15], v[14:15], v[244:245]
	v_pk_add_f32 v[16:17], v[16:17], v[246:247]
	global_store_dwordx4 v[220:221], v[14:17], off offset:224
	s_mov_b32 s3, 0
	s_add_i32 s7, s7, 1
	v_mov_b32_e32 v114, 0
	v_mov_b32_e32 v115, 0
	v_mov_b32_e32 v116, 0
	v_mov_b32_e32 v117, 0
	v_mov_b32_e32 v118, 0
	v_mov_b32_e32 v119, 0
	v_mov_b32_e32 v120, 0
	v_mov_b32_e32 v121, 0
	v_mov_b32_e32 v122, 0
	v_mov_b32_e32 v123, 0
	v_mov_b32_e32 v124, 0
	v_mov_b32_e32 v125, 0
	v_mov_b32_e32 v126, 0
	v_mov_b32_e32 v127, 0
	v_mov_b32_e32 v128, 0
	v_mov_b32_e32 v129, 0
	v_mov_b32_e32 v98, 0
	v_mov_b32_e32 v99, 0
	v_mov_b32_e32 v100, 0
	v_mov_b32_e32 v101, 0
	v_mov_b32_e32 v102, 0
	v_mov_b32_e32 v103, 0
	v_mov_b32_e32 v104, 0
	v_mov_b32_e32 v105, 0
	v_mov_b32_e32 v106, 0
	v_mov_b32_e32 v107, 0
	v_mov_b32_e32 v108, 0
	v_mov_b32_e32 v109, 0
	v_mov_b32_e32 v110, 0
	v_mov_b32_e32 v111, 0
	v_mov_b32_e32 v112, 0
	v_mov_b32_e32 v113, 0
	v_mov_b32_e32 v82, 0
	v_mov_b32_e32 v83, 0
	v_mov_b32_e32 v84, 0
	v_mov_b32_e32 v85, 0
	v_mov_b32_e32 v86, 0
	v_mov_b32_e32 v87, 0
	v_mov_b32_e32 v88, 0
	v_mov_b32_e32 v89, 0
	v_mov_b32_e32 v90, 0
	v_mov_b32_e32 v91, 0
	v_mov_b32_e32 v92, 0
	v_mov_b32_e32 v93, 0
	v_mov_b32_e32 v94, 0
	v_mov_b32_e32 v95, 0
	v_mov_b32_e32 v96, 0
	v_mov_b32_e32 v97, 0
	v_mov_b32_e32 v66, 0
	v_mov_b32_e32 v67, 0
	v_mov_b32_e32 v68, 0
	v_mov_b32_e32 v69, 0
	v_mov_b32_e32 v70, 0
	v_mov_b32_e32 v71, 0
	v_mov_b32_e32 v72, 0
	v_mov_b32_e32 v73, 0
	v_mov_b32_e32 v74, 0
	v_mov_b32_e32 v75, 0
	v_mov_b32_e32 v76, 0
	v_mov_b32_e32 v77, 0
	v_mov_b32_e32 v78, 0
	v_mov_b32_e32 v79, 0
	v_mov_b32_e32 v80, 0
	v_mov_b32_e32 v81, 0
	v_mov_b32_e32 v50, 0
	v_mov_b32_e32 v51, 0
	v_mov_b32_e32 v52, 0
	v_mov_b32_e32 v53, 0
	v_mov_b32_e32 v54, 0
	v_mov_b32_e32 v55, 0
	v_mov_b32_e32 v56, 0
	v_mov_b32_e32 v57, 0
	v_mov_b32_e32 v58, 0
	v_mov_b32_e32 v59, 0
	v_mov_b32_e32 v60, 0
	v_mov_b32_e32 v61, 0
	v_mov_b32_e32 v62, 0
	v_mov_b32_e32 v63, 0
	v_mov_b32_e32 v64, 0
	v_mov_b32_e32 v65, 0
	v_mov_b32_e32 v34, 0
	v_mov_b32_e32 v35, 0
	v_mov_b32_e32 v36, 0
	v_mov_b32_e32 v37, 0
	v_mov_b32_e32 v38, 0
	v_mov_b32_e32 v39, 0
	v_mov_b32_e32 v40, 0
	v_mov_b32_e32 v41, 0
	v_mov_b32_e32 v42, 0
	v_mov_b32_e32 v43, 0
	v_mov_b32_e32 v44, 0
	v_mov_b32_e32 v45, 0
	v_mov_b32_e32 v46, 0
	v_mov_b32_e32 v47, 0
	v_mov_b32_e32 v48, 0
	v_mov_b32_e32 v49, 0
	v_mov_b32_e32 v18, 0
	v_mov_b32_e32 v19, 0
	v_mov_b32_e32 v20, 0
	v_mov_b32_e32 v21, 0
	v_mov_b32_e32 v22, 0
	v_mov_b32_e32 v23, 0
	v_mov_b32_e32 v24, 0
	v_mov_b32_e32 v25, 0
	v_mov_b32_e32 v26, 0
	v_mov_b32_e32 v27, 0
	v_mov_b32_e32 v28, 0
	v_mov_b32_e32 v29, 0
	v_mov_b32_e32 v30, 0
	v_mov_b32_e32 v31, 0
	v_mov_b32_e32 v32, 0
	v_mov_b32_e32 v33, 0
	v_mov_b32_e32 v2, 0
	v_mov_b32_e32 v3, 0
	v_mov_b32_e32 v4, 0
	v_mov_b32_e32 v5, 0
	v_mov_b32_e32 v6, 0
	v_mov_b32_e32 v7, 0
	v_mov_b32_e32 v8, 0
	v_mov_b32_e32 v9, 0
	v_mov_b32_e32 v10, 0
	v_mov_b32_e32 v11, 0
	v_mov_b32_e32 v12, 0
	v_mov_b32_e32 v13, 0
	v_mov_b32_e32 v14, 0
	v_mov_b32_e32 v15, 0
	v_mov_b32_e32 v16, 0
	v_mov_b32_e32 v17, 0
	s_setprio 0
	s_cmp_ge_i32 s7, s6
	s_cbranch_scc0 .LBB0_64

.LBB0_807:
	s_setprio 3
	s_mul_i32 s3, s9, s82
	s_add_i32 s3, s3, s63
	s_ashr_i32 s5, s3, 31
	s_lshr_b32 s5, s5, 28
	s_add_i32 s5, s3, s5
	s_ashr_i32 s10, s5, 4
	s_and_b32 s5, s5, -16
	s_sub_i32 s3, s3, s5
	s_lshl_b32 s5, s10, 1
	s_and_b32 s10, s3, 1
	s_or_b32 s5, s10, s5
	v_readlane_b32 s10, v252, 35
	s_sub_i32 s12, 0x7f, s5
	v_readlane_b32 s11, v252, 36
	s_and_b64 s[10:11], s[10:11], exec
	s_cselect_b32 s10, s12, s5
	v_mov_b32_e32 v0, v222
	s_ashr_i32 s11, s10, 31
	v_and_b32_e32 v190, 0xffffff80, v0
	s_lshl_b64 s[10:11], s[10:11], 8
	v_ashrrev_i32_e32 v191, 31, v190
	v_lshl_add_u64 v[190:191], s[10:11], 0, v[190:191]
	s_lshl_b32 s3, s3, 6
	v_and_b32_e32 v185, 64, v0
	v_and_or_b32 v190, v0, 31, v190
	s_and_b32 s3, s3, 0xffffff80
	v_lshrrev_b32_e32 v0, 3, v0
	s_ashr_i32 s5, s3, 31
	v_and_b32_e32 v0, 4, v0
	v_or3_b32 v192, v0, v185, s3
	v_mov_b32_e32 v193, s5
	v_lshlrev_b64 v[190:191], 10, v[190:191]
	v_lshl_add_u64 v[190:191], v[190:191], 0, v[192:193]
	v_lshlrev_b64 v[190:191], 2, v[190:191]
	v_lshl_add_u64 v[196:197], s[0:1], 0, v[190:191]
	s_mov_b64 s[98:99], 0x20000
	v_readlane_b32 s12, v252, 31
	v_readlane_b32 s13, v252, 32
	v_lshl_add_u64 v[220:221], s[12:13], 0, v[190:191]
	v_lshl_add_u64 v[192:193], v[196:197], 0, 0
	global_load_dwordx4 v[194:197], v[192:193], off
	global_load_dwordx4 v[198:201], v[192:193], off offset:32
	global_load_dwordx4 v[202:205], v[192:193], off offset:64
	global_load_dwordx4 v[206:209], v[192:193], off offset:96
	global_load_dwordx4 v[216:219], v[192:193], off offset:128
	global_load_dwordx4 v[236:239], v[192:193], off offset:160
	global_load_dwordx4 v[240:243], v[192:193], off offset:192
	global_load_dwordx4 v[244:247], v[192:193], off offset:224
	s_waitcnt vmcnt(7)
	v_pk_fma_f32 v[98:99], v[98:99], 0.5, v[194:195] op_sel_hi:[1,0,1]
	v_pk_fma_f32 v[100:101], v[100:101], 0.5, v[196:197] op_sel_hi:[1,0,1]
	global_store_dwordx4 v[220:221], v[98:101], off
	v_lshl_add_u64 v[192:193], v[192:193], 0, s[98:99]
	global_load_dwordx4 v[194:197], v[192:193], off
	s_waitcnt vmcnt(8)
	v_pk_fma_f32 v[102:103], v[102:103], 0.5, v[198:199] op_sel_hi:[1,0,1]
	v_pk_fma_f32 v[104:105], v[104:105], 0.5, v[200:201] op_sel_hi:[1,0,1]
	global_store_dwordx4 v[220:221], v[102:105], off offset:32
	global_load_dwordx4 v[198:201], v[192:193], off offset:32
	s_waitcnt vmcnt(9)
	v_pk_fma_f32 v[106:107], v[106:107], 0.5, v[202:203] op_sel_hi:[1,0,1]
	v_pk_fma_f32 v[108:109], v[108:109], 0.5, v[204:205] op_sel_hi:[1,0,1]
	global_store_dwordx4 v[220:221], v[106:109], off offset:64
	global_load_dwordx4 v[202:205], v[192:193], off offset:64
	s_waitcnt vmcnt(10)
	v_pk_fma_f32 v[110:111], v[110:111], 0.5, v[206:207] op_sel_hi:[1,0,1]
	v_pk_fma_f32 v[112:113], v[112:113], 0.5, v[208:209] op_sel_hi:[1,0,1]
	global_store_dwordx4 v[220:221], v[110:113], off offset:96
	global_load_dwordx4 v[206:209], v[192:193], off offset:96
	s_waitcnt vmcnt(11)
	v_pk_fma_f32 v[114:115], v[114:115], 0.5, v[216:217] op_sel_hi:[1,0,1]
	v_pk_fma_f32 v[116:117], v[116:117], 0.5, v[218:219] op_sel_hi:[1,0,1]
	global_store_dwordx4 v[220:221], v[114:117], off offset:128
	global_load_dwordx4 v[216:219], v[192:193], off offset:128
	s_waitcnt vmcnt(12)
	v_pk_fma_f32 v[118:119], v[118:119], 0.5, v[236:237] op_sel_hi:[1,0,1]
	v_pk_fma_f32 v[120:121], v[120:121], 0.5, v[238:239] op_sel_hi:[1,0,1]
	global_store_dwordx4 v[220:221], v[118:121], off offset:160
	global_load_dwordx4 v[236:239], v[192:193], off offset:160
	s_waitcnt vmcnt(13)
	v_pk_fma_f32 v[122:123], v[122:123], 0.5, v[240:241] op_sel_hi:[1,0,1]
	v_pk_fma_f32 v[124:125], v[124:125], 0.5, v[242:243] op_sel_hi:[1,0,1]
	global_store_dwordx4 v[220:221], v[122:125], off offset:192
	global_load_dwordx4 v[240:243], v[192:193], off offset:192
	s_waitcnt vmcnt(14)
	v_pk_fma_f32 v[126:127], v[126:127], 0.5, v[244:245] op_sel_hi:[1,0,1]
	v_pk_fma_f32 v[128:129], v[128:129], 0.5, v[246:247] op_sel_hi:[1,0,1]
	global_store_dwordx4 v[220:221], v[126:129], off offset:224
	global_load_dwordx4 v[244:247], v[192:193], off offset:224
	s_waitcnt vmcnt(14)
	v_pk_fma_f32 v[82:83], v[82:83], 0.5, v[194:195] op_sel_hi:[1,0,1]
	v_pk_fma_f32 v[84:85], v[84:85], 0.5, v[196:197] op_sel_hi:[1,0,1]
	v_lshl_add_u64 v[220:221], v[220:221], 0, s[98:99]
	global_store_dwordx4 v[220:221], v[82:85], off
	v_lshl_add_u64 v[192:193], v[192:193], 0, s[98:99]
	global_load_dwordx4 v[194:197], v[192:193], off
	s_waitcnt vmcnt(14)
	v_pk_fma_f32 v[86:87], v[86:87], 0.5, v[198:199] op_sel_hi:[1,0,1]
	v_pk_fma_f32 v[88:89], v[88:89], 0.5, v[200:201] op_sel_hi:[1,0,1]
	global_store_dwordx4 v[220:221], v[86:89], off offset:32
	global_load_dwordx4 v[198:201], v[192:193], off offset:32
	s_waitcnt vmcnt(14)
	v_pk_fma_f32 v[90:91], v[90:91], 0.5, v[202:203] op_sel_hi:[1,0,1]
	v_pk_fma_f32 v[92:93], v[92:93], 0.5, v[204:205] op_sel_hi:[1,0,1]
	global_store_dwordx4 v[220:221], v[90:93], off offset:64
	global_load_dwordx4 v[202:205], v[192:193], off offset:64
	s_waitcnt vmcnt(14)
	v_pk_fma_f32 v[94:95], v[94:95], 0.5, v[206:207] op_sel_hi:[1,0,1]
	v_pk_fma_f32 v[96:97], v[96:97], 0.5, v[208:209] op_sel_hi:[1,0,1]
	global_store_dwordx4 v[220:221], v[94:97], off offset:96
	global_load_dwordx4 v[206:209], v[192:193], off offset:96
	s_waitcnt vmcnt(14)
	v_pk_fma_f32 v[66:67], v[66:67], 0.5, v[216:217] op_sel_hi:[1,0,1]
	v_pk_fma_f32 v[68:69], v[68:69], 0.5, v[218:219] op_sel_hi:[1,0,1]
	global_store_dwordx4 v[220:221], v[66:69], off offset:128
	global_load_dwordx4 v[216:219], v[192:193], off offset:128
	s_waitcnt vmcnt(14)
	v_pk_fma_f32 v[70:71], v[70:71], 0.5, v[236:237] op_sel_hi:[1,0,1]
	v_pk_fma_f32 v[72:73], v[72:73], 0.5, v[238:239] op_sel_hi:[1,0,1]
	global_store_dwordx4 v[220:221], v[70:73], off offset:160
	global_load_dwordx4 v[236:239], v[192:193], off offset:160
	s_waitcnt vmcnt(14)
	v_pk_fma_f32 v[74:75], v[74:75], 0.5, v[240:241] op_sel_hi:[1,0,1]
	v_pk_fma_f32 v[76:77], v[76:77], 0.5, v[242:243] op_sel_hi:[1,0,1]
	global_store_dwordx4 v[220:221], v[74:77], off offset:192
	global_load_dwordx4 v[240:243], v[192:193], off offset:192
	s_waitcnt vmcnt(14)
	v_pk_fma_f32 v[78:79], v[78:79], 0.5, v[244:245] op_sel_hi:[1,0,1]
	v_pk_fma_f32 v[80:81], v[80:81], 0.5, v[246:247] op_sel_hi:[1,0,1]
	global_store_dwordx4 v[220:221], v[78:81], off offset:224
	global_load_dwordx4 v[244:247], v[192:193], off offset:224
	s_waitcnt vmcnt(14)
	v_pk_fma_f32 v[50:51], v[50:51], 0.5, v[194:195] op_sel_hi:[1,0,1]
	v_pk_fma_f32 v[52:53], v[52:53], 0.5, v[196:197] op_sel_hi:[1,0,1]
	v_lshl_add_u64 v[220:221], v[220:221], 0, s[98:99]
	global_store_dwordx4 v[220:221], v[50:53], off
	v_lshl_add_u64 v[192:193], v[192:193], 0, s[98:99]
	global_load_dwordx4 v[194:197], v[192:193], off
	s_waitcnt vmcnt(14)
	v_pk_fma_f32 v[54:55], v[54:55], 0.5, v[198:199] op_sel_hi:[1,0,1]
	v_pk_fma_f32 v[56:57], v[56:57], 0.5, v[200:201] op_sel_hi:[1,0,1]
	global_store_dwordx4 v[220:221], v[54:57], off offset:32
	global_load_dwordx4 v[198:201], v[192:193], off offset:32
	s_waitcnt vmcnt(14)
	v_pk_fma_f32 v[58:59], v[58:59], 0.5, v[202:203] op_sel_hi:[1,0,1]
	v_pk_fma_f32 v[60:61], v[60:61], 0.5, v[204:205] op_sel_hi:[1,0,1]
	global_store_dwordx4 v[220:221], v[58:61], off offset:64
	global_load_dwordx4 v[202:205], v[192:193], off offset:64
	s_waitcnt vmcnt(14)
	v_pk_fma_f32 v[62:63], v[62:63], 0.5, v[206:207] op_sel_hi:[1,0,1]
	v_pk_fma_f32 v[64:65], v[64:65], 0.5, v[208:209] op_sel_hi:[1,0,1]
	global_store_dwordx4 v[220:221], v[62:65], off offset:96
	global_load_dwordx4 v[206:209], v[192:193], off offset:96
	s_waitcnt vmcnt(14)
	v_pk_fma_f32 v[34:35], v[34:35], 0.5, v[216:217] op_sel_hi:[1,0,1]
	v_pk_fma_f32 v[36:37], v[36:37], 0.5, v[218:219] op_sel_hi:[1,0,1]
	global_store_dwordx4 v[220:221], v[34:37], off offset:128
	global_load_dwordx4 v[216:219], v[192:193], off offset:128
	s_waitcnt vmcnt(14)
	v_pk_fma_f32 v[38:39], v[38:39], 0.5, v[236:237] op_sel_hi:[1,0,1]
	v_pk_fma_f32 v[40:41], v[40:41], 0.5, v[238:239] op_sel_hi:[1,0,1]
	global_store_dwordx4 v[220:221], v[38:41], off offset:160
	global_load_dwordx4 v[236:239], v[192:193], off offset:160
	s_waitcnt vmcnt(14)
	v_pk_fma_f32 v[42:43], v[42:43], 0.5, v[240:241] op_sel_hi:[1,0,1]
	v_pk_fma_f32 v[44:45], v[44:45], 0.5, v[242:243] op_sel_hi:[1,0,1]
	global_store_dwordx4 v[220:221], v[42:45], off offset:192
	global_load_dwordx4 v[240:243], v[192:193], off offset:192
	s_waitcnt vmcnt(14)
	v_pk_fma_f32 v[46:47], v[46:47], 0.5, v[244:245] op_sel_hi:[1,0,1]
	v_pk_fma_f32 v[48:49], v[48:49], 0.5, v[246:247] op_sel_hi:[1,0,1]
	global_store_dwordx4 v[220:221], v[46:49], off offset:224
	global_load_dwordx4 v[244:247], v[192:193], off offset:224
	s_waitcnt vmcnt(14)
	v_pk_fma_f32 v[18:19], v[18:19], 0.5, v[194:195] op_sel_hi:[1,0,1]
	v_pk_fma_f32 v[20:21], v[20:21], 0.5, v[196:197] op_sel_hi:[1,0,1]
	v_lshl_add_u64 v[220:221], v[220:221], 0, s[98:99]
	global_store_dwordx4 v[220:221], v[18:21], off
	s_waitcnt vmcnt(13)
	v_pk_fma_f32 v[22:23], v[22:23], 0.5, v[198:199] op_sel_hi:[1,0,1]
	v_pk_fma_f32 v[24:25], v[24:25], 0.5, v[200:201] op_sel_hi:[1,0,1]
	global_store_dwordx4 v[220:221], v[22:25], off offset:32
	s_waitcnt vmcnt(12)
	v_pk_fma_f32 v[26:27], v[26:27], 0.5, v[202:203] op_sel_hi:[1,0,1]
	v_pk_fma_f32 v[28:29], v[28:29], 0.5, v[204:205] op_sel_hi:[1,0,1]
	global_store_dwordx4 v[220:221], v[26:29], off offset:64
	s_waitcnt vmcnt(11)
	v_pk_fma_f32 v[30:31], v[30:31], 0.5, v[206:207] op_sel_hi:[1,0,1]
	v_pk_fma_f32 v[32:33], v[32:33], 0.5, v[208:209] op_sel_hi:[1,0,1]
	global_store_dwordx4 v[220:221], v[30:33], off offset:96
	s_waitcnt vmcnt(10)
	v_pk_fma_f32 v[2:3], v[2:3], 0.5, v[216:217] op_sel_hi:[1,0,1]
	v_pk_fma_f32 v[4:5], v[4:5], 0.5, v[218:219] op_sel_hi:[1,0,1]
	global_store_dwordx4 v[220:221], v[2:5], off offset:128
	s_waitcnt vmcnt(9)
	v_pk_fma_f32 v[6:7], v[6:7], 0.5, v[236:237] op_sel_hi:[1,0,1]
	v_pk_fma_f32 v[8:9], v[8:9], 0.5, v[238:239] op_sel_hi:[1,0,1]
	global_store_dwordx4 v[220:221], v[6:9], off offset:160
	s_waitcnt vmcnt(8)
	v_pk_fma_f32 v[10:11], v[10:11], 0.5, v[240:241] op_sel_hi:[1,0,1]
	v_pk_fma_f32 v[12:13], v[12:13], 0.5, v[242:243] op_sel_hi:[1,0,1]
	global_store_dwordx4 v[220:221], v[10:13], off offset:192
	s_waitcnt vmcnt(7)
	v_pk_fma_f32 v[14:15], v[14:15], 0.5, v[244:245] op_sel_hi:[1,0,1]
	v_pk_fma_f32 v[16:17], v[16:17], 0.5, v[246:247] op_sel_hi:[1,0,1]
	global_store_dwordx4 v[220:221], v[14:17], off offset:224
	s_add_i32 s9, s9, 1
	s_mov_b32 s5, 0
	v_mov_b32_e32 v98, 0
	v_mov_b32_e32 v99, 0
	v_mov_b32_e32 v100, 0
	v_mov_b32_e32 v101, 0
	v_mov_b32_e32 v102, 0
	v_mov_b32_e32 v103, 0
	v_mov_b32_e32 v104, 0
	v_mov_b32_e32 v105, 0
	v_mov_b32_e32 v106, 0
	v_mov_b32_e32 v107, 0
	v_mov_b32_e32 v108, 0
	v_mov_b32_e32 v109, 0
	v_mov_b32_e32 v110, 0
	v_mov_b32_e32 v111, 0
	v_mov_b32_e32 v112, 0
	v_mov_b32_e32 v113, 0
	v_mov_b32_e32 v114, 0
	v_mov_b32_e32 v115, 0
	v_mov_b32_e32 v116, 0
	v_mov_b32_e32 v117, 0
	v_mov_b32_e32 v118, 0
	v_mov_b32_e32 v119, 0
	v_mov_b32_e32 v120, 0
	v_mov_b32_e32 v121, 0
	v_mov_b32_e32 v122, 0
	v_mov_b32_e32 v123, 0
	v_mov_b32_e32 v124, 0
	v_mov_b32_e32 v125, 0
	v_mov_b32_e32 v126, 0
	v_mov_b32_e32 v127, 0
	v_mov_b32_e32 v128, 0
	v_mov_b32_e32 v129, 0
	v_mov_b32_e32 v82, 0
	v_mov_b32_e32 v83, 0
	v_mov_b32_e32 v84, 0
	v_mov_b32_e32 v85, 0
	v_mov_b32_e32 v86, 0
	v_mov_b32_e32 v87, 0
	v_mov_b32_e32 v88, 0
	v_mov_b32_e32 v89, 0
	v_mov_b32_e32 v90, 0
	v_mov_b32_e32 v91, 0
	v_mov_b32_e32 v92, 0
	v_mov_b32_e32 v93, 0
	v_mov_b32_e32 v94, 0
	v_mov_b32_e32 v95, 0
	v_mov_b32_e32 v96, 0
	v_mov_b32_e32 v97, 0
	v_mov_b32_e32 v66, 0
	v_mov_b32_e32 v67, 0
	v_mov_b32_e32 v68, 0
	v_mov_b32_e32 v69, 0
	v_mov_b32_e32 v70, 0
	v_mov_b32_e32 v71, 0
	v_mov_b32_e32 v72, 0
	v_mov_b32_e32 v73, 0
	v_mov_b32_e32 v74, 0
	v_mov_b32_e32 v75, 0
	v_mov_b32_e32 v76, 0
	v_mov_b32_e32 v77, 0
	v_mov_b32_e32 v78, 0
	v_mov_b32_e32 v79, 0
	v_mov_b32_e32 v80, 0
	v_mov_b32_e32 v81, 0
	v_mov_b32_e32 v50, 0
	v_mov_b32_e32 v51, 0
	v_mov_b32_e32 v52, 0
	v_mov_b32_e32 v53, 0
	v_mov_b32_e32 v54, 0
	v_mov_b32_e32 v55, 0
	v_mov_b32_e32 v56, 0
	v_mov_b32_e32 v57, 0
	v_mov_b32_e32 v58, 0
	v_mov_b32_e32 v59, 0
	v_mov_b32_e32 v60, 0
	v_mov_b32_e32 v61, 0
	v_mov_b32_e32 v62, 0
	v_mov_b32_e32 v63, 0
	v_mov_b32_e32 v64, 0
	v_mov_b32_e32 v65, 0
	v_mov_b32_e32 v34, 0
	v_mov_b32_e32 v35, 0
	v_mov_b32_e32 v36, 0
	v_mov_b32_e32 v37, 0
	v_mov_b32_e32 v38, 0
	v_mov_b32_e32 v39, 0
	v_mov_b32_e32 v40, 0
	v_mov_b32_e32 v41, 0
	v_mov_b32_e32 v42, 0
	v_mov_b32_e32 v43, 0
	v_mov_b32_e32 v44, 0
	v_mov_b32_e32 v45, 0
	v_mov_b32_e32 v46, 0
	v_mov_b32_e32 v47, 0
	v_mov_b32_e32 v48, 0
	v_mov_b32_e32 v49, 0
	v_mov_b32_e32 v18, 0
	v_mov_b32_e32 v19, 0
	v_mov_b32_e32 v20, 0
	v_mov_b32_e32 v21, 0
	v_mov_b32_e32 v22, 0
	v_mov_b32_e32 v23, 0
	v_mov_b32_e32 v24, 0
	v_mov_b32_e32 v25, 0
	v_mov_b32_e32 v26, 0
	v_mov_b32_e32 v27, 0
	v_mov_b32_e32 v28, 0
	v_mov_b32_e32 v29, 0
	v_mov_b32_e32 v30, 0
	v_mov_b32_e32 v31, 0
	v_mov_b32_e32 v32, 0
	v_mov_b32_e32 v33, 0
	v_mov_b32_e32 v2, 0
	v_mov_b32_e32 v3, 0
	v_mov_b32_e32 v4, 0
	v_mov_b32_e32 v5, 0
	v_mov_b32_e32 v6, 0
	v_mov_b32_e32 v7, 0
	v_mov_b32_e32 v8, 0
	v_mov_b32_e32 v9, 0
	v_mov_b32_e32 v10, 0
	v_mov_b32_e32 v11, 0
	v_mov_b32_e32 v12, 0
	v_mov_b32_e32 v13, 0
	v_mov_b32_e32 v14, 0
	v_mov_b32_e32 v15, 0
	v_mov_b32_e32 v16, 0
	v_mov_b32_e32 v17, 0
	s_setprio 0
	s_cmp_ge_i32 s9, s8
	s_cbranch_scc0 .LBB0_803

.LBB0_821:
	s_setprio 3
	s_mul_i32 s1, s5, s82
	s_add_i32 s1, s1, s63
	s_mul_hi_i32 s3, s1, 0x2e8ba2e9
	s_lshr_b32 s8, s3, 31
	s_ashr_i32 s3, s3, 4
	s_add_i32 s3, s3, s8
	s_mul_i32 s8, s3, 0x58
	s_sub_i32 s1, s1, s8
	s_lshl_b32 s3, s3, 1
	s_and_b32 s8, s1, 1
	s_or_b32 s3, s8, s3
	v_readlane_b32 s8, v252, 35
	s_sub_i32 s10, 0x7f, s3
	v_readlane_b32 s9, v252, 36
	s_and_b64 s[8:9], s[8:9], exec
	s_cselect_b32 s8, s10, s3
	v_mov_b32_e32 v0, v222
	s_ashr_i32 s9, s8, 31
	v_and_b32_e32 v192, 0xffffff80, v0
	s_lshl_b64 s[8:9], s[8:9], 8
	v_ashrrev_i32_e32 v193, 31, v192
	s_lshl_b32 s1, s1, 6
	v_lshl_add_u64 v[192:193], s[8:9], 0, v[192:193]
	v_readlane_b32 s8, v252, 45
	s_and_b32 s1, s1, 0xffffff80
	v_readlane_b32 s9, v252, 46
	v_and_or_b32 v185, v0, 64, s1
	v_lshrrev_b32_e32 v190, 3, v0
	v_and_or_b32 v0, v0, 31, v192
	v_mov_b64_e32 v[194:195], s[8:9]
	s_movk_i32 s1, 0x1600
	v_mad_u64_u32 v[194:195], s[8:9], v0, s1, v[194:195]
	v_mul_f32_e32 v0, 0xbfb8aa3b, v114
	v_exp_f32_e32 v0, v0
	v_mad_i32_i24 v195, v193, s1, v195
	v_ashrrev_i32_e32 v185, 1, v185
	v_and_or_b32 v190, v190, 4, v185
	v_add_f32_e32 v0, 1.0, v0
	v_rcp_f32_e32 v192, v0
	v_mul_f32_e32 v0, 0xbfb8aa3b, v115
	v_exp_f32_e32 v0, v0
	v_ashrrev_i32_e32 v191, 31, v190
	v_lshl_add_u64 v[190:191], v[190:191], 1, v[194:195]
	s_mov_b32 s1, 0x2c000
	v_add_f32_e32 v0, 1.0, v0
	v_rcp_f32_e32 v193, v0
	v_mul_f32_e32 v0, 0xbfb8aa3b, v116
	v_exp_f32_e32 v0, v0
	s_mov_b64 s[8:9], 0x2c000
	v_pk_mul_f32 v[114:115], v[114:115], v[192:193]
	s_mov_b32 s3, 0
	v_add_f32_e32 v0, 1.0, v0
	v_pk_mul_f32 v[98:99], v[98:99], v[114:115]
	v_rcp_f32_e32 v114, v0
	v_mul_f32_e32 v0, 0xbfb8aa3b, v117
	v_exp_f32_e32 v0, v0
	v_cvt_pk_bf16_f32 v98, v98, v99
	s_add_i32 s5, s5, 1
	v_add_f32_e32 v0, 1.0, v0
	v_rcp_f32_e32 v115, v0
	v_mul_f32_e32 v0, 0xbfb8aa3b, v118
	v_exp_f32_e32 v0, v0
	v_pk_mul_f32 v[114:115], v[116:117], v[114:115]
	s_nop 0
	v_pk_mul_f32 v[100:101], v[100:101], v[114:115]
	v_add_f32_e32 v0, 1.0, v0
	v_cvt_pk_bf16_f32 v99, v100, v101
	global_store_dwordx2 v[190:191], v[98:99], off
	v_rcp_f32_e32 v98, v0
	v_mul_f32_e32 v0, 0xbfb8aa3b, v119
	v_exp_f32_e32 v0, v0
	v_mov_b32_e32 v114, 0
	v_mov_b32_e32 v115, v114
	v_mov_b32_e32 v116, v114
	v_add_f32_e32 v0, 1.0, v0
	v_rcp_f32_e32 v99, v0
	v_mul_f32_e32 v0, 0xbfb8aa3b, v120
	v_exp_f32_e32 v0, v0
	v_mov_b32_e32 v117, v114
	v_pk_mul_f32 v[98:99], v[118:119], v[98:99]
	v_mov_b32_e32 v118, v114
	v_add_f32_e32 v0, 1.0, v0
	v_rcp_f32_e32 v100, v0
	v_mul_f32_e32 v0, 0xbfb8aa3b, v121
	v_exp_f32_e32 v0, v0
	v_pk_mul_f32 v[98:99], v[102:103], v[98:99]
	v_mov_b32_e32 v119, v114
	v_cvt_pk_bf16_f32 v98, v98, v99
	v_add_f32_e32 v0, 1.0, v0
	v_rcp_f32_e32 v101, v0
	v_mul_f32_e32 v0, 0xbfb8aa3b, v122
	v_exp_f32_e32 v0, v0
	v_mov_b32_e32 v102, v114
	v_pk_mul_f32 v[100:101], v[120:121], v[100:101]
	v_mov_b32_e32 v120, v114
	v_pk_mul_f32 v[100:101], v[104:105], v[100:101]
	v_add_f32_e32 v0, 1.0, v0
	v_cvt_pk_bf16_f32 v99, v100, v101
	global_store_dwordx2 v[190:191], v[98:99], off offset:16
	v_rcp_f32_e32 v98, v0
	v_mul_f32_e32 v0, 0xbfb8aa3b, v123
	v_exp_f32_e32 v0, v0
	v_mov_b32_e32 v121, v114
	v_mov_b32_e32 v103, v114
	v_mov_b32_e32 v104, v114
	v_add_f32_e32 v0, 1.0, v0
	v_rcp_f32_e32 v99, v0
	v_mul_f32_e32 v0, 0xbfb8aa3b, v124
	v_exp_f32_e32 v0, v0
	v_mov_b32_e32 v105, v114
	v_pk_mul_f32 v[98:99], v[122:123], v[98:99]
	v_mov_b32_e32 v122, v114
	v_add_f32_e32 v0, 1.0, v0
	v_rcp_f32_e32 v100, v0
	v_mul_f32_e32 v0, 0xbfb8aa3b, v125
	v_exp_f32_e32 v0, v0
	v_pk_mul_f32 v[98:99], v[106:107], v[98:99]
	v_mov_b32_e32 v123, v114
	v_cvt_pk_bf16_f32 v98, v98, v99
	v_add_f32_e32 v0, 1.0, v0
	v_rcp_f32_e32 v101, v0
	v_mul_f32_e32 v0, 0xbfb8aa3b, v126
	v_exp_f32_e32 v0, v0
	v_mov_b32_e32 v106, v114
	v_pk_mul_f32 v[100:101], v[124:125], v[100:101]
	v_mov_b32_e32 v124, v114
	v_pk_mul_f32 v[100:101], v[108:109], v[100:101]
	v_add_f32_e32 v0, 1.0, v0
	v_cvt_pk_bf16_f32 v99, v100, v101
	global_store_dwordx2 v[190:191], v[98:99], off offset:32
	v_rcp_f32_e32 v98, v0
	v_mul_f32_e32 v0, 0xbfb8aa3b, v127
	v_exp_f32_e32 v0, v0
	v_mov_b32_e32 v125, v114
	v_mov_b32_e32 v107, v114
	v_mov_b32_e32 v108, v114
	v_add_f32_e32 v0, 1.0, v0
	v_rcp_f32_e32 v99, v0
	v_mul_f32_e32 v0, 0xbfb8aa3b, v128
	v_exp_f32_e32 v0, v0
	v_mov_b32_e32 v109, v114
	v_pk_mul_f32 v[98:99], v[126:127], v[98:99]
	v_mov_b32_e32 v126, v114
	v_add_f32_e32 v0, 1.0, v0
	v_rcp_f32_e32 v100, v0
	v_mul_f32_e32 v0, 0xbfb8aa3b, v129
	v_exp_f32_e32 v0, v0
	v_pk_mul_f32 v[98:99], v[110:111], v[98:99]
	v_mov_b32_e32 v127, v114
	v_cvt_pk_bf16_f32 v98, v98, v99
	v_add_f32_e32 v0, 1.0, v0
	v_rcp_f32_e32 v101, v0
	v_mul_f32_e32 v0, 0xbfb8aa3b, v82
	v_exp_f32_e32 v0, v0
	v_mov_b32_e32 v110, v114
	v_pk_mul_f32 v[100:101], v[128:129], v[100:101]
	v_mov_b32_e32 v128, v114
	v_pk_mul_f32 v[100:101], v[112:113], v[100:101]
	v_add_f32_e32 v0, 1.0, v0
	v_cvt_pk_bf16_f32 v99, v100, v101
	v_rcp_f32_e32 v100, v0
	v_mul_f32_e32 v0, 0xbfb8aa3b, v83
	v_exp_f32_e32 v0, v0
	global_store_dwordx2 v[190:191], v[98:99], off offset:48
	v_lshl_add_u64 v[98:99], v[190:191], 0, s[8:9]
	s_mov_b64 s[8:9], 0x58000
	v_add_f32_e32 v0, 1.0, v0
	v_rcp_f32_e32 v101, v0
	v_mul_f32_e32 v0, 0xbfb8aa3b, v84
	v_exp_f32_e32 v0, v0
	v_mov_b32_e32 v129, v114
	v_pk_mul_f32 v[82:83], v[82:83], v[100:101]
	v_mov_b32_e32 v100, v114
	v_add_f32_e32 v0, 1.0, v0
	v_pk_mul_f32 v[66:67], v[66:67], v[82:83]
	v_rcp_f32_e32 v82, v0
	v_mul_f32_e32 v0, 0xbfb8aa3b, v85
	v_exp_f32_e32 v0, v0
	v_cvt_pk_bf16_f32 v66, v66, v67
	v_mov_b32_e32 v101, v114
	v_mov_b32_e32 v111, v114
	v_add_f32_e32 v0, 1.0, v0
	v_rcp_f32_e32 v83, v0
	v_mul_f32_e32 v0, 0xbfb8aa3b, v86
	v_exp_f32_e32 v0, v0
	v_mov_b32_e32 v112, v114
	v_pk_mul_f32 v[82:83], v[84:85], v[82:83]
	v_mov_b32_e32 v113, v114
	v_pk_mul_f32 v[68:69], v[68:69], v[82:83]
	v_add_f32_e32 v0, 1.0, v0
	v_cvt_pk_bf16_f32 v67, v68, v69
	v_add_co_u32_e32 v68, vcc, s1, v190
	s_mov_b32 s1, 0x58000
	s_nop 0
	v_addc_co_u32_e32 v69, vcc, 0, v191, vcc
	global_store_dwordx2 v[68:69], v[66:67], off
	v_rcp_f32_e32 v66, v0
	v_mul_f32_e32 v0, 0xbfb8aa3b, v87
	v_exp_f32_e32 v0, v0
	v_mov_b32_e32 v82, v114
	v_mov_b32_e32 v83, v114
	v_mov_b32_e32 v84, v114
	v_add_f32_e32 v0, 1.0, v0
	v_rcp_f32_e32 v67, v0
	v_mul_f32_e32 v0, 0xbfb8aa3b, v88
	v_exp_f32_e32 v0, v0
	v_mov_b32_e32 v85, v114
	v_pk_mul_f32 v[66:67], v[86:87], v[66:67]
	v_mov_b32_e32 v86, v114
	v_add_f32_e32 v0, 1.0, v0
	v_rcp_f32_e32 v68, v0
	v_mul_f32_e32 v0, 0xbfb8aa3b, v89
	v_exp_f32_e32 v0, v0
	v_pk_mul_f32 v[66:67], v[70:71], v[66:67]
	v_mov_b32_e32 v87, v114
	v_cvt_pk_bf16_f32 v66, v66, v67
	v_add_f32_e32 v0, 1.0, v0
	v_rcp_f32_e32 v69, v0
	v_mul_f32_e32 v0, 0xbfb8aa3b, v90
	v_exp_f32_e32 v0, v0
	v_mov_b32_e32 v70, v114
	v_pk_mul_f32 v[68:69], v[88:89], v[68:69]
	v_mov_b32_e32 v88, v114
	v_pk_mul_f32 v[68:69], v[72:73], v[68:69]
	v_add_f32_e32 v0, 1.0, v0
	v_cvt_pk_bf16_f32 v67, v68, v69
	global_store_dwordx2 v[98:99], v[66:67], off offset:16
	v_rcp_f32_e32 v66, v0
	v_mul_f32_e32 v0, 0xbfb8aa3b, v91
	v_exp_f32_e32 v0, v0
	v_mov_b32_e32 v89, v114
	v_mov_b32_e32 v71, v114
	v_mov_b32_e32 v72, v114
	v_add_f32_e32 v0, 1.0, v0
	v_rcp_f32_e32 v67, v0
	v_mul_f32_e32 v0, 0xbfb8aa3b, v92
	v_exp_f32_e32 v0, v0
	v_mov_b32_e32 v73, v114
	v_pk_mul_f32 v[66:67], v[90:91], v[66:67]
	v_mov_b32_e32 v90, v114
	v_add_f32_e32 v0, 1.0, v0
	v_rcp_f32_e32 v68, v0
	v_mul_f32_e32 v0, 0xbfb8aa3b, v93
	v_exp_f32_e32 v0, v0
	v_pk_mul_f32 v[66:67], v[74:75], v[66:67]
	v_mov_b32_e32 v91, v114
	v_cvt_pk_bf16_f32 v66, v66, v67
	v_add_f32_e32 v0, 1.0, v0
	v_rcp_f32_e32 v69, v0
	v_mul_f32_e32 v0, 0xbfb8aa3b, v94
	v_exp_f32_e32 v0, v0
	v_mov_b32_e32 v74, v114
	v_pk_mul_f32 v[68:69], v[92:93], v[68:69]
	v_mov_b32_e32 v92, v114
	v_pk_mul_f32 v[68:69], v[76:77], v[68:69]
	v_add_f32_e32 v0, 1.0, v0
	v_cvt_pk_bf16_f32 v67, v68, v69
	global_store_dwordx2 v[98:99], v[66:67], off offset:32
	v_rcp_f32_e32 v66, v0
	v_mul_f32_e32 v0, 0xbfb8aa3b, v95
	v_exp_f32_e32 v0, v0
	v_mov_b32_e32 v93, v114
	v_mov_b32_e32 v75, v114
	v_mov_b32_e32 v76, v114
	v_add_f32_e32 v0, 1.0, v0
	v_rcp_f32_e32 v67, v0
	v_mul_f32_e32 v0, 0xbfb8aa3b, v96
	v_exp_f32_e32 v0, v0
	v_mov_b32_e32 v77, v114
	v_pk_mul_f32 v[66:67], v[94:95], v[66:67]
	v_mov_b32_e32 v94, v114
	v_add_f32_e32 v0, 1.0, v0
	v_rcp_f32_e32 v68, v0
	v_mul_f32_e32 v0, 0xbfb8aa3b, v97
	v_exp_f32_e32 v0, v0
	v_pk_mul_f32 v[66:67], v[78:79], v[66:67]
	v_mov_b32_e32 v95, v114
	v_cvt_pk_bf16_f32 v66, v66, v67
	v_add_f32_e32 v0, 1.0, v0
	v_rcp_f32_e32 v69, v0
	v_mul_f32_e32 v0, 0xbfb8aa3b, v50
	v_exp_f32_e32 v0, v0
	v_mov_b32_e32 v78, v114
	v_pk_mul_f32 v[68:69], v[96:97], v[68:69]
	v_mov_b32_e32 v96, v114
	v_pk_mul_f32 v[68:69], v[80:81], v[68:69]
	v_add_f32_e32 v0, 1.0, v0
	v_cvt_pk_bf16_f32 v67, v68, v69
	v_rcp_f32_e32 v68, v0
	v_mul_f32_e32 v0, 0xbfb8aa3b, v51
	v_exp_f32_e32 v0, v0
	global_store_dwordx2 v[98:99], v[66:67], off offset:48
	v_lshl_add_u64 v[66:67], v[190:191], 0, s[8:9]
	s_mov_b64 s[8:9], 0x84000
	v_add_f32_e32 v0, 1.0, v0
	v_rcp_f32_e32 v69, v0
	v_mul_f32_e32 v0, 0xbfb8aa3b, v52
	v_exp_f32_e32 v0, v0
	v_mov_b32_e32 v98, v114
	v_pk_mul_f32 v[50:51], v[50:51], v[68:69]
	v_mov_b32_e32 v99, v114
	v_add_f32_e32 v0, 1.0, v0
	v_pk_mul_f32 v[34:35], v[34:35], v[50:51]
	v_rcp_f32_e32 v50, v0
	v_mul_f32_e32 v0, 0xbfb8aa3b, v53
	v_exp_f32_e32 v0, v0
	v_cvt_pk_bf16_f32 v34, v34, v35
	v_mov_b32_e32 v97, v114
	v_mov_b32_e32 v68, v114
	v_add_f32_e32 v0, 1.0, v0
	v_rcp_f32_e32 v51, v0
	v_mul_f32_e32 v0, 0xbfb8aa3b, v54
	v_exp_f32_e32 v0, v0
	v_mov_b32_e32 v69, v114
	v_pk_mul_f32 v[50:51], v[52:53], v[50:51]
	v_mov_b32_e32 v79, v114
	v_pk_mul_f32 v[36:37], v[36:37], v[50:51]
	v_add_f32_e32 v0, 1.0, v0
	v_cvt_pk_bf16_f32 v35, v36, v37
	v_add_co_u32_e32 v36, vcc, s1, v190
	s_mov_b32 s1, 0x84000
	s_nop 0
	v_addc_co_u32_e32 v37, vcc, 0, v191, vcc
	global_store_dwordx2 v[36:37], v[34:35], off
	v_rcp_f32_e32 v34, v0
	v_mul_f32_e32 v0, 0xbfb8aa3b, v55
	v_exp_f32_e32 v0, v0
	v_mov_b32_e32 v80, v114
	v_mov_b32_e32 v81, v114
	v_mov_b32_e32 v50, v114
	v_add_f32_e32 v0, 1.0, v0
	v_rcp_f32_e32 v35, v0
	v_mul_f32_e32 v0, 0xbfb8aa3b, v56
	v_exp_f32_e32 v0, v0
	v_mov_b32_e32 v51, v114
	v_pk_mul_f32 v[34:35], v[54:55], v[34:35]
	v_mov_b32_e32 v52, v114
	v_add_f32_e32 v0, 1.0, v0
	v_rcp_f32_e32 v36, v0
	v_mul_f32_e32 v0, 0xbfb8aa3b, v57
	v_exp_f32_e32 v0, v0
	v_pk_mul_f32 v[34:35], v[38:39], v[34:35]
	v_mov_b32_e32 v53, v114
	v_cvt_pk_bf16_f32 v34, v34, v35
	v_add_f32_e32 v0, 1.0, v0
	v_rcp_f32_e32 v37, v0
	v_mul_f32_e32 v0, 0xbfb8aa3b, v58
	v_exp_f32_e32 v0, v0
	v_mov_b32_e32 v54, v114
	v_pk_mul_f32 v[36:37], v[56:57], v[36:37]
	v_mov_b32_e32 v55, v114
	v_pk_mul_f32 v[36:37], v[40:41], v[36:37]
	v_add_f32_e32 v0, 1.0, v0
	v_cvt_pk_bf16_f32 v35, v36, v37
	global_store_dwordx2 v[66:67], v[34:35], off offset:16
	v_rcp_f32_e32 v34, v0
	v_mul_f32_e32 v0, 0xbfb8aa3b, v59
	v_exp_f32_e32 v0, v0
	v_mov_b32_e32 v56, v114
	v_mov_b32_e32 v57, v114
	v_mov_b32_e32 v38, v114
	v_add_f32_e32 v0, 1.0, v0
	v_rcp_f32_e32 v35, v0
	v_mul_f32_e32 v0, 0xbfb8aa3b, v60
	v_exp_f32_e32 v0, v0
	v_mov_b32_e32 v39, v114
	v_pk_mul_f32 v[34:35], v[58:59], v[34:35]
	v_mov_b32_e32 v58, v114
	v_add_f32_e32 v0, 1.0, v0
	v_rcp_f32_e32 v36, v0
	v_mul_f32_e32 v0, 0xbfb8aa3b, v61
	v_exp_f32_e32 v0, v0
	v_pk_mul_f32 v[34:35], v[42:43], v[34:35]
	v_mov_b32_e32 v59, v114
	v_cvt_pk_bf16_f32 v34, v34, v35
	v_add_f32_e32 v0, 1.0, v0
	v_rcp_f32_e32 v37, v0
	v_mul_f32_e32 v0, 0xbfb8aa3b, v62
	v_exp_f32_e32 v0, v0
	v_mov_b32_e32 v40, v114
	v_pk_mul_f32 v[36:37], v[60:61], v[36:37]
	v_mov_b32_e32 v60, v114
	v_pk_mul_f32 v[36:37], v[44:45], v[36:37]
	v_add_f32_e32 v0, 1.0, v0
	v_cvt_pk_bf16_f32 v35, v36, v37
	global_store_dwordx2 v[66:67], v[34:35], off offset:32
	v_rcp_f32_e32 v34, v0
	v_mul_f32_e32 v0, 0xbfb8aa3b, v63
	v_exp_f32_e32 v0, v0
	v_mov_b32_e32 v61, v114
	v_mov_b32_e32 v41, v114
	v_mov_b32_e32 v42, v114
	v_add_f32_e32 v0, 1.0, v0
	v_rcp_f32_e32 v35, v0
	v_mul_f32_e32 v0, 0xbfb8aa3b, v64
	v_exp_f32_e32 v0, v0
	v_mov_b32_e32 v43, v114
	v_pk_mul_f32 v[34:35], v[62:63], v[34:35]
	v_mov_b32_e32 v62, v114
	v_add_f32_e32 v0, 1.0, v0
	v_rcp_f32_e32 v36, v0
	v_mul_f32_e32 v0, 0xbfb8aa3b, v65
	v_exp_f32_e32 v0, v0
	v_pk_mul_f32 v[34:35], v[46:47], v[34:35]
	v_mov_b32_e32 v63, v114
	v_cvt_pk_bf16_f32 v34, v34, v35
	v_add_f32_e32 v0, 1.0, v0
	v_rcp_f32_e32 v37, v0
	v_mul_f32_e32 v0, 0xbfb8aa3b, v18
	v_exp_f32_e32 v0, v0
	v_mov_b32_e32 v44, v114
	v_pk_mul_f32 v[36:37], v[64:65], v[36:37]
	v_mov_b32_e32 v64, v114
	v_pk_mul_f32 v[36:37], v[48:49], v[36:37]
	v_add_f32_e32 v0, 1.0, v0
	v_cvt_pk_bf16_f32 v35, v36, v37
	v_rcp_f32_e32 v36, v0
	v_mul_f32_e32 v0, 0xbfb8aa3b, v19
	v_exp_f32_e32 v0, v0
	global_store_dwordx2 v[66:67], v[34:35], off offset:48
	v_lshl_add_u64 v[34:35], v[190:191], 0, s[8:9]
	v_mov_b32_e32 v66, v114
	v_add_f32_e32 v0, 1.0, v0
	v_rcp_f32_e32 v37, v0
	v_mul_f32_e32 v0, 0xbfb8aa3b, v20
	v_exp_f32_e32 v0, v0
	v_mov_b32_e32 v67, v114
	v_pk_mul_f32 v[18:19], v[18:19], v[36:37]
	v_mov_b32_e32 v65, v114
	v_add_f32_e32 v0, 1.0, v0
	v_pk_mul_f32 v[2:3], v[2:3], v[18:19]
	v_rcp_f32_e32 v18, v0
	v_mul_f32_e32 v0, 0xbfb8aa3b, v21
	v_exp_f32_e32 v0, v0
	v_cvt_pk_bf16_f32 v2, v2, v3
	v_mov_b32_e32 v36, v114
	v_mov_b32_e32 v37, v114
	v_add_f32_e32 v0, 1.0, v0
	v_rcp_f32_e32 v19, v0
	v_mul_f32_e32 v0, 0xbfb8aa3b, v22
	v_exp_f32_e32 v0, v0
	v_mov_b32_e32 v45, v114
	v_pk_mul_f32 v[18:19], v[20:21], v[18:19]
	v_mov_b32_e32 v46, v114
	v_pk_mul_f32 v[4:5], v[4:5], v[18:19]
	v_add_f32_e32 v0, 1.0, v0
	v_cvt_pk_bf16_f32 v3, v4, v5
	v_add_co_u32_e32 v4, vcc, s1, v190
	v_mov_b32_e32 v47, v114
	s_nop 0
	v_addc_co_u32_e32 v5, vcc, 0, v191, vcc
	global_store_dwordx2 v[4:5], v[2:3], off
	v_rcp_f32_e32 v2, v0
	v_mul_f32_e32 v0, 0xbfb8aa3b, v23
	v_exp_f32_e32 v0, v0
	v_mov_b32_e32 v48, v114
	v_mov_b32_e32 v49, v114
	v_mov_b32_e32 v18, v114
	v_add_f32_e32 v0, 1.0, v0
	v_rcp_f32_e32 v3, v0
	v_mul_f32_e32 v0, 0xbfb8aa3b, v24
	v_exp_f32_e32 v0, v0
	v_mov_b32_e32 v19, v114
	v_pk_mul_f32 v[2:3], v[22:23], v[2:3]
	v_mov_b32_e32 v20, v114
	v_add_f32_e32 v0, 1.0, v0
	v_rcp_f32_e32 v4, v0
	v_mul_f32_e32 v0, 0xbfb8aa3b, v25
	v_exp_f32_e32 v0, v0
	v_pk_mul_f32 v[2:3], v[6:7], v[2:3]
	v_mov_b32_e32 v21, v114
	v_cvt_pk_bf16_f32 v2, v2, v3
	v_add_f32_e32 v0, 1.0, v0
	v_rcp_f32_e32 v5, v0
	v_mul_f32_e32 v0, 0xbfb8aa3b, v26
	v_exp_f32_e32 v0, v0
	v_mov_b32_e32 v22, v114
	v_pk_mul_f32 v[4:5], v[24:25], v[4:5]
	v_mov_b32_e32 v23, v114
	v_pk_mul_f32 v[4:5], v[8:9], v[4:5]
	v_add_f32_e32 v0, 1.0, v0
	v_cvt_pk_bf16_f32 v3, v4, v5
	global_store_dwordx2 v[34:35], v[2:3], off offset:16
	v_rcp_f32_e32 v2, v0
	v_mul_f32_e32 v0, 0xbfb8aa3b, v27
	v_exp_f32_e32 v0, v0
	v_mov_b32_e32 v24, v114
	v_mov_b32_e32 v25, v114
	v_mov_b32_e32 v6, v114
	v_add_f32_e32 v0, 1.0, v0
	v_rcp_f32_e32 v3, v0
	v_mul_f32_e32 v0, 0xbfb8aa3b, v28
	v_exp_f32_e32 v0, v0
	v_mov_b32_e32 v7, v114
	v_pk_mul_f32 v[2:3], v[26:27], v[2:3]
	v_mov_b32_e32 v26, v114
	v_add_f32_e32 v0, 1.0, v0
	v_rcp_f32_e32 v4, v0
	v_mul_f32_e32 v0, 0xbfb8aa3b, v29
	v_exp_f32_e32 v0, v0
	v_pk_mul_f32 v[2:3], v[10:11], v[2:3]
	v_mov_b32_e32 v27, v114
	v_cvt_pk_bf16_f32 v2, v2, v3
	v_add_f32_e32 v0, 1.0, v0
	v_rcp_f32_e32 v5, v0
	v_mul_f32_e32 v0, 0xbfb8aa3b, v30
	v_exp_f32_e32 v0, v0
	v_mov_b32_e32 v8, v114
	v_pk_mul_f32 v[4:5], v[28:29], v[4:5]
	v_mov_b32_e32 v28, v114
	v_pk_mul_f32 v[4:5], v[12:13], v[4:5]
	v_add_f32_e32 v0, 1.0, v0
	v_cvt_pk_bf16_f32 v3, v4, v5
	global_store_dwordx2 v[34:35], v[2:3], off offset:32
	v_rcp_f32_e32 v2, v0
	v_mul_f32_e32 v0, 0xbfb8aa3b, v31
	v_exp_f32_e32 v0, v0
	v_mov_b32_e32 v29, v114
	v_mov_b32_e32 v9, v114
	v_mov_b32_e32 v10, v114
	v_add_f32_e32 v0, 1.0, v0
	v_rcp_f32_e32 v3, v0
	v_mul_f32_e32 v0, 0xbfb8aa3b, v32
	v_exp_f32_e32 v0, v0
	v_mov_b32_e32 v11, v114
	v_pk_mul_f32 v[2:3], v[30:31], v[2:3]
	v_mov_b32_e32 v30, v114
	v_add_f32_e32 v0, 1.0, v0
	v_rcp_f32_e32 v4, v0
	v_mul_f32_e32 v0, 0xbfb8aa3b, v33
	v_exp_f32_e32 v0, v0
	v_pk_mul_f32 v[2:3], v[14:15], v[2:3]
	v_mov_b32_e32 v31, v114
	v_cvt_pk_bf16_f32 v2, v2, v3
	v_add_f32_e32 v0, 1.0, v0
	v_rcp_f32_e32 v5, v0
	v_mov_b32_e32 v12, v114
	v_mov_b32_e32 v13, v114
	v_mov_b32_e32 v14, v114
	v_pk_mul_f32 v[4:5], v[32:33], v[4:5]
	v_mov_b32_e32 v32, v114
	v_pk_mul_f32 v[4:5], v[16:17], v[4:5]
	v_mov_b32_e32 v33, v114
	v_cvt_pk_bf16_f32 v3, v4, v5
	global_store_dwordx2 v[34:35], v[2:3], off offset:48
	v_mov_b32_e32 v34, v114
	v_mov_b32_e32 v35, v114
	v_mov_b32_e32 v2, v114
	v_mov_b32_e32 v3, v114
	v_mov_b32_e32 v4, v114
	v_mov_b32_e32 v5, v114
	v_mov_b32_e32 v15, v114
	v_mov_b32_e32 v16, v114
	v_mov_b32_e32 v17, v114
	s_setprio 0
	s_cmp_ge_i32 s5, s4
	s_cbranch_scc0 .LBB0_817
